# GEMM K-loops: progressive counted lgkmcnt waits at the head of 18 straight-line MFMA blocks (each MFMA waits only for its own LDS fragments)
# speedup vs baseline: 1.0063x; 1.0003x over previous
; #define G8_STAGE(bufoff, gbase, voff) do { _Pragma("unroll") for (int _i = 0; _i < 2; ++_i) \
;         __builtin_amdgcn_global_load_lds((const unsigned*)((const char*)(gbase) + (voff)[_i]), (LAS unsigned*)(lds + (bufoff) + ldsw + _i * 8192), 16, 0, 0); } while (0)
; #define G8_LDA(dst, b, h) do { _Pragma("unroll") for (int m = 0; m < 4; ++m) _Pragma("unroll") for (int k = 0; k < 2; ++k) dst[m][k] = *(const LAS bf16x8*)(lds + G8_SA(b, h) + aoff + m * 2048 + k * 1024); } while (0)
; #define G8_LDB(dst, b, h) do { _Pragma("unroll") for (int n = 0; n < 2; ++n) _Pragma("unroll") for (int k = 0; k < 2; ++k) dst[n][k] = *(const LAS bf16x8*)(lds + G8_SB(b, h) + boff + n * 2048 + k * 1024); } while (0)
; #define G8_MMA(ai, bj, At, Bt) do { __builtin_amdgcn_s_setprio(1); _Pragma("unroll") for (int m = 0; m < 4; ++m) _Pragma("unroll") for (int n = 0; n < 2; ++n) _Pragma("unroll") for (int k = 0; k < 2; ++k) \
;         acc[ai][bj][m][n] = __builtin_amdgcn_mfma_f32_16x16x32_bf16(Bt[n][k], At[m][k], acc[ai][bj][m][n], 0, 0, 0); __builtin_amdgcn_s_setprio(0); } while (0)
; #define G8_WAIT_V(n) asm volatile("s_waitcnt vmcnt(" #n ")" ::: "memory")
; #define G8_WAIT_L(n) asm volatile("s_waitcnt lgkmcnt(" #n ")" ::: "memory")
; template <class Epi, class Sched>
; __device__ __forceinline__ void gemm_phase(int wv, LAS unsigned char* lds, const int K, const Sched& S, const Epi& E) {
;     ...
;         for (int t = 0; t < nt; t += 2) {
;             const bool last = (t == nt - 2);
;             const char* a1 = cA + (size_t)(t + 1) * kstep;
;             const char* a2 = last ? nA : cA + (size_t)(t + 2) * kstep; const char* b2 = last ? nB : cB + (size_t)(t + 2) * kstep;
;             const char* a3 = a2 + kstep; const char* b3 = b2 + kstep;
;             G8_LDB(B0, 0, 0); G8_SCHED; G8_LDA(At, 0, 0); G8_STAGE(G8_SA(1, 1), a1 + hstep, voffA);
;             G8_WAIT_L(8); G8_BAR; G8_WAIT_L(0); G8_MMA(0, 0, At, B0); G8_BAR; G8_SCHED;
;             G8_LDB(B1, 0, 1); G8_STAGE(G8_SB(0, 0), b2, voffB);
;             G8_BAR; G8_WAIT_L(0); G8_MMA(0, 1, At, B1); G8_BAR;
;             if (full) G8_LDA(At, 0, 1); G8_STAGE(G8_SA(0, 0), a2, voffA);
;             G8_BAR; G8_WAIT_L(0); if (full) G8_MMA(1, 0, At, B0); G8_BAR; G8_SCHED;
;             G8_STAGE(G8_SB(0, 1), b2 + hstep, voffB);
;             G8_WAIT_V(6); G8_BAR; if (full) G8_MMA(1, 1, At, B1); G8_BAR;
.LBB0_448:
	s_add_u32 s5, s42, s12
	s_addc_u32 s38, s43, s13
	s_add_i32 s76, 0, 0x10000
	v_add_u32_e32 v0, s76, v248
	ds_read_b128 v[180:183], v0
	ds_read_b128 v[184:187], v0 offset:1024
	ds_read_b128 v[188:191], v0 offset:2048
	ds_read_b128 v[192:195], v0 offset:3072
	s_cmpk_eq_i32 s12, 0x700
	s_cselect_b64 s[40:41], -1, 0
	s_and_b64 s[8:9], s[40:41], exec
	s_cselect_b32 s39, s35, s38
	s_cselect_b32 s38, s34, s5
	v_lshl_add_u64 v[164:165], v[2:3], 0, s[12:13]
	s_add_i32 m0, s48, 0xc000
	s_waitcnt lgkmcnt(0)
	ds_read_b128 v[144:147], v249
	ds_read_b128 v[160:163], v249 offset:1024
	ds_read_b128 v[140:143], v249 offset:2048
	ds_read_b128 v[156:159], v249 offset:3072
	ds_read_b128 v[136:139], v249 offset:4096
	ds_read_b128 v[152:155], v249 offset:5120
	ds_read_b128 v[132:135], v249 offset:6144
	ds_read_b128 v[148:151], v249 offset:7168
	global_load_lds_dwordx4 v[164:165], off
	v_lshl_add_u64 v[164:165], v[218:219], 0, s[12:13]
	s_add_i32 m0, s48, 0xe000
	s_nop 0
	global_load_lds_dwordx4 v[164:165], off
	s_waitcnt lgkmcnt(8)
	s_barrier
	s_waitcnt lgkmcnt(7)
	v_mfma_f32_16x16x32_bf16 v[128:131], v[180:183], v[144:147], v[128:131]
	v_mfma_f32_16x16x32_bf16 v[124:127], v[188:191], v[144:147], v[124:127]
	s_waitcnt lgkmcnt(5)
	v_mfma_f32_16x16x32_bf16 v[120:123], v[180:183], v[140:143], v[120:123]
	v_mfma_f32_16x16x32_bf16 v[116:119], v[188:191], v[140:143], v[116:119]
	s_waitcnt lgkmcnt(3)
	v_mfma_f32_16x16x32_bf16 v[112:115], v[180:183], v[136:139], v[112:115]
	v_mfma_f32_16x16x32_bf16 v[108:111], v[188:191], v[136:139], v[108:111]
	s_waitcnt lgkmcnt(1)
	v_mfma_f32_16x16x32_bf16 v[104:107], v[180:183], v[132:135], v[104:107]
	v_mfma_f32_16x16x32_bf16 v[100:103], v[188:191], v[132:135], v[100:103]
	v_mfma_f32_16x16x32_bf16 v[128:131], v[184:187], v[160:163], v[128:131]
	v_mfma_f32_16x16x32_bf16 v[124:127], v[192:195], v[160:163], v[124:127]
	v_mfma_f32_16x16x32_bf16 v[120:123], v[184:187], v[156:159], v[120:123]
	v_mfma_f32_16x16x32_bf16 v[116:119], v[192:195], v[156:159], v[116:119]
	v_mfma_f32_16x16x32_bf16 v[112:115], v[184:187], v[152:155], v[112:115]
	v_mfma_f32_16x16x32_bf16 v[108:111], v[192:195], v[152:155], v[108:111]
	s_waitcnt lgkmcnt(0)
	v_mfma_f32_16x16x32_bf16 v[104:107], v[184:187], v[148:151], v[104:107]
	v_mfma_f32_16x16x32_bf16 v[100:103], v[192:195], v[148:151], v[100:103]
	s_barrier
	v_add_u32_e32 v0, 0, v248
	s_add_i32 s5, s76, s25
	v_add_u32_e32 v176, 0x14000, v0
	v_lshl_add_u64 v[220:221], s[38:39], 0, v[208:209]
	s_mov_b32 m0, s5
	ds_read_b128 v[164:167], v176
	ds_read_b128 v[168:171], v176 offset:1024
	ds_read_b128 v[172:175], v176 offset:2048
	ds_read_b128 v[176:179], v176 offset:3072
	global_load_lds_dwordx4 v[220:221], off
	v_lshl_add_u64 v[222:223], s[38:39], 0, v[212:213]
	s_add_i32 m0, s5, 0x2000
	s_nop 0
	global_load_lds_dwordx4 v[222:223], off
	s_barrier
	s_waitcnt lgkmcnt(3)
	v_mfma_f32_16x16x32_bf16 v[96:99], v[164:167], v[144:147], v[96:99]
	s_waitcnt lgkmcnt(1)
	v_mfma_f32_16x16x32_bf16 v[92:95], v[172:175], v[144:147], v[92:95]
	v_mfma_f32_16x16x32_bf16 v[88:91], v[164:167], v[140:143], v[88:91]
	v_mfma_f32_16x16x32_bf16 v[84:87], v[172:175], v[140:143], v[84:87]
	v_mfma_f32_16x16x32_bf16 v[80:83], v[164:167], v[136:139], v[80:83]
	v_mfma_f32_16x16x32_bf16 v[76:79], v[172:175], v[136:139], v[76:79]
	v_mfma_f32_16x16x32_bf16 v[72:75], v[164:167], v[132:135], v[72:75]
	v_mfma_f32_16x16x32_bf16 v[68:71], v[172:175], v[132:135], v[68:71]
	v_mfma_f32_16x16x32_bf16 v[96:99], v[168:171], v[160:163], v[96:99]
	s_waitcnt lgkmcnt(0)
	v_mfma_f32_16x16x32_bf16 v[92:95], v[176:179], v[160:163], v[92:95]
	v_mfma_f32_16x16x32_bf16 v[88:91], v[168:171], v[156:159], v[88:91]
	v_mfma_f32_16x16x32_bf16 v[84:87], v[176:179], v[156:159], v[84:87]
	v_mfma_f32_16x16x32_bf16 v[80:83], v[168:171], v[152:155], v[80:83]
	v_mfma_f32_16x16x32_bf16 v[76:79], v[176:179], v[152:155], v[76:79]
	v_mfma_f32_16x16x32_bf16 v[72:75], v[168:171], v[148:151], v[72:75]
	v_mfma_f32_16x16x32_bf16 v[68:71], v[176:179], v[148:151], v[68:71]
	v_cndmask_b32_e64 v198, 0, 1, s[10:11]
	v_cmp_ne_u32_e64 s[8:9], 1, v198
	s_andn2_b64 vcc, exec, s[10:11]
	s_barrier
	s_cbranch_vccnz .LBB0_450
	ds_read_b128 v[144:147], v249 offset:16384
	ds_read_b128 v[160:163], v249 offset:17408
	ds_read_b128 v[140:143], v249 offset:18432
	ds_read_b128 v[156:159], v249 offset:19456
	ds_read_b128 v[136:139], v249 offset:20480
	ds_read_b128 v[152:155], v249 offset:21504
	ds_read_b128 v[132:135], v249 offset:22528
	ds_read_b128 v[148:151], v249 offset:23552

; #define G8_STAGE(bufoff, gbase, voff) do { _Pragma("unroll") for (int _i = 0; _i < 2; ++_i) \
;         __builtin_amdgcn_global_load_lds((const unsigned*)((const char*)(gbase) + (voff)[_i]), (LAS unsigned*)(lds + (bufoff) + ldsw + _i * 8192), 16, 0, 0); } while (0)
; #define G8_LDA(dst, b, h) do { _Pragma("unroll") for (int m = 0; m < 4; ++m) _Pragma("unroll") for (int k = 0; k < 2; ++k) dst[m][k] = *(const LAS bf16x8*)(lds + G8_SA(b, h) + aoff + m * 2048 + k * 1024); } while (0)
; #define G8_LDB(dst, b, h) do { _Pragma("unroll") for (int n = 0; n < 2; ++n) _Pragma("unroll") for (int k = 0; k < 2; ++k) dst[n][k] = *(const LAS bf16x8*)(lds + G8_SB(b, h) + boff + n * 2048 + k * 1024); } while (0)
; #define G8_MMA(ai, bj, At, Bt) do { __builtin_amdgcn_s_setprio(1); _Pragma("unroll") for (int m = 0; m < 4; ++m) _Pragma("unroll") for (int n = 0; n < 2; ++n) _Pragma("unroll") for (int k = 0; k < 2; ++k) \
;         acc[ai][bj][m][n] = __builtin_amdgcn_mfma_f32_16x16x32_bf16(Bt[n][k], At[m][k], acc[ai][bj][m][n], 0, 0, 0); __builtin_amdgcn_s_setprio(0); } while (0)
; #define G8_WAIT_V(n) asm volatile("s_waitcnt vmcnt(" #n ")" ::: "memory")
; #define G8_WAIT_L(n) asm volatile("s_waitcnt lgkmcnt(" #n ")" ::: "memory")
; #define G8_BAR __builtin_amdgcn_s_barrier()
; #define G8_SCHED __builtin_amdgcn_sched_barrier(0)
; template <class Epi, class Sched>
; __device__ __forceinline__ void gemm_phase(int wv, LAS unsigned char* lds, const int K, const Sched& S, const Epi& E) {
;     ...
;             G8_LDB(B0, 1, 0); G8_SCHED; G8_LDA(At, 1, 0); G8_STAGE(G8_SA(0, 1), a2 + hstep, voffA);
;             G8_WAIT_L(8); G8_BAR; G8_WAIT_L(0); G8_MMA(0, 0, At, B0); G8_BAR; G8_SCHED;
;             G8_LDB(B1, 1, 1); G8_STAGE(G8_SB(1, 0), b3, voffB);
;             G8_BAR; G8_WAIT_L(0); G8_MMA(0, 1, At, B1); G8_BAR;
;             if (full) G8_LDA(At, 1, 1); G8_STAGE(G8_SA(1, 0), a3, voffA);
;             G8_BAR; G8_WAIT_L(0); if (full) G8_MMA(1, 0, At, B0); G8_BAR; G8_SCHED;
;             G8_STAGE(G8_SB(1, 1), b3 + hstep, voffB);
;             G8_WAIT_V(6); G8_BAR; if (full) G8_MMA(1, 1, At, B1); G8_BAR;
.LBB0_454:
	s_add_i32 s5, 0, 0x18000
	s_waitcnt lgkmcnt(0)
	v_add_u32_e32 v132, s5, v248
	s_barrier
	ds_read_b128 v[180:183], v132
	ds_read_b128 v[184:187], v132 offset:1024
	ds_read_b128 v[188:191], v132 offset:2048
	ds_read_b128 v[192:195], v132 offset:3072
	s_add_u32 s40, s40, 0x40000
	s_addc_u32 s41, s41, 0
	s_mov_b32 m0, s52
	v_lshl_add_u64 v[164:165], s[40:41], 0, v[206:207]
	ds_read_b128 v[144:147], v249 offset:32768
	ds_read_b128 v[160:163], v249 offset:33792
	ds_read_b128 v[140:143], v249 offset:34816
	ds_read_b128 v[156:159], v249 offset:35840
	ds_read_b128 v[136:139], v249 offset:36864
	ds_read_b128 v[152:155], v249 offset:37888
	ds_read_b128 v[132:135], v249 offset:38912
	ds_read_b128 v[148:151], v249 offset:39936
	global_load_lds_dwordx4 v[164:165], off
	v_lshl_add_u64 v[164:165], s[40:41], 0, v[210:211]
	s_mov_b32 m0, s53
	s_nop 0
	global_load_lds_dwordx4 v[164:165], off
	s_waitcnt lgkmcnt(8)
	s_barrier
	s_waitcnt lgkmcnt(7)
	v_mfma_f32_16x16x32_bf16 v[128:131], v[180:183], v[144:147], v[128:131]
	v_mfma_f32_16x16x32_bf16 v[124:127], v[188:191], v[144:147], v[124:127]
	s_waitcnt lgkmcnt(5)
	v_mfma_f32_16x16x32_bf16 v[120:123], v[180:183], v[140:143], v[120:123]
	v_mfma_f32_16x16x32_bf16 v[116:119], v[188:191], v[140:143], v[116:119]
	s_waitcnt lgkmcnt(3)
	v_mfma_f32_16x16x32_bf16 v[112:115], v[180:183], v[136:139], v[112:115]
	v_mfma_f32_16x16x32_bf16 v[108:111], v[188:191], v[136:139], v[108:111]
	s_waitcnt lgkmcnt(1)
	v_mfma_f32_16x16x32_bf16 v[104:107], v[180:183], v[132:135], v[104:107]
	v_mfma_f32_16x16x32_bf16 v[100:103], v[188:191], v[132:135], v[100:103]
	v_mfma_f32_16x16x32_bf16 v[128:131], v[184:187], v[160:163], v[128:131]
	v_mfma_f32_16x16x32_bf16 v[124:127], v[192:195], v[160:163], v[124:127]
	v_mfma_f32_16x16x32_bf16 v[120:123], v[184:187], v[156:159], v[120:123]
	v_mfma_f32_16x16x32_bf16 v[116:119], v[192:195], v[156:159], v[116:119]
	v_mfma_f32_16x16x32_bf16 v[112:115], v[184:187], v[152:155], v[112:115]
	v_mfma_f32_16x16x32_bf16 v[108:111], v[192:195], v[152:155], v[108:111]
	s_waitcnt lgkmcnt(0)
	v_mfma_f32_16x16x32_bf16 v[104:107], v[184:187], v[148:151], v[104:107]
	v_mfma_f32_16x16x32_bf16 v[100:103], v[192:195], v[148:151], v[100:103]
	s_barrier
	s_add_i32 s5, s5, s25
	v_add_u32_e32 v0, 0x1c000, v0
	v_lshl_add_u64 v[198:199], v[220:221], 0, s[58:59]
	s_mov_b32 m0, s5
	ds_read_b128 v[164:167], v0
	ds_read_b128 v[168:171], v0 offset:1024
	ds_read_b128 v[172:175], v0 offset:2048
	ds_read_b128 v[176:179], v0 offset:3072
	global_load_lds_dwordx4 v[198:199], off
	v_lshl_add_u64 v[198:199], v[222:223], 0, s[58:59]
	s_add_i32 m0, s5, 0x2000
	s_nop 0
	global_load_lds_dwordx4 v[198:199], off
	s_barrier
	s_waitcnt lgkmcnt(3)
	v_mfma_f32_16x16x32_bf16 v[96:99], v[164:167], v[144:147], v[96:99]
	s_waitcnt lgkmcnt(1)
	v_mfma_f32_16x16x32_bf16 v[92:95], v[172:175], v[144:147], v[92:95]
	v_mfma_f32_16x16x32_bf16 v[88:91], v[164:167], v[140:143], v[88:91]
	v_mfma_f32_16x16x32_bf16 v[84:87], v[172:175], v[140:143], v[84:87]
	v_mfma_f32_16x16x32_bf16 v[80:83], v[164:167], v[136:139], v[80:83]
	v_mfma_f32_16x16x32_bf16 v[76:79], v[172:175], v[136:139], v[76:79]
	v_mfma_f32_16x16x32_bf16 v[72:75], v[164:167], v[132:135], v[72:75]
	v_mfma_f32_16x16x32_bf16 v[68:71], v[172:175], v[132:135], v[68:71]
	v_mfma_f32_16x16x32_bf16 v[96:99], v[168:171], v[160:163], v[96:99]
	s_waitcnt lgkmcnt(0)
	v_mfma_f32_16x16x32_bf16 v[92:95], v[176:179], v[160:163], v[92:95]
	v_mfma_f32_16x16x32_bf16 v[88:91], v[168:171], v[156:159], v[88:91]
	v_mfma_f32_16x16x32_bf16 v[84:87], v[176:179], v[156:159], v[84:87]
	v_mfma_f32_16x16x32_bf16 v[80:83], v[168:171], v[152:155], v[80:83]
	v_mfma_f32_16x16x32_bf16 v[76:79], v[176:179], v[152:155], v[76:79]
	v_mfma_f32_16x16x32_bf16 v[72:75], v[168:171], v[148:151], v[72:75]
	v_mfma_f32_16x16x32_bf16 v[68:71], v[176:179], v[148:151], v[68:71]
	s_and_b64 vcc, exec, s[8:9]
	s_mov_b32 s94, 0x3a800000
	s_barrier
	s_cbranch_vccnz .LBB0_456
	ds_read_b128 v[144:147], v249 offset:49152
	ds_read_b128 v[160:163], v249 offset:50176
	ds_read_b128 v[140:143], v249 offset:51200
	ds_read_b128 v[156:159], v249 offset:52224
	ds_read_b128 v[136:139], v249 offset:53248
	ds_read_b128 v[152:155], v249 offset:54272
	ds_read_b128 v[132:135], v249 offset:55296
	ds_read_b128 v[148:151], v249 offset:56320

; #define G8_STAGE(bufoff, gbase, voff) do { _Pragma("unroll") for (int _i = 0; _i < 2; ++_i) \
;         __builtin_amdgcn_global_load_lds((const unsigned*)((const char*)(gbase) + (voff)[_i]), (LAS unsigned*)(lds + (bufoff) + ldsw + _i * 8192), 16, 0, 0); } while (0)
; #define G8_LDA(dst, b, h) do { _Pragma("unroll") for (int m = 0; m < 4; ++m) _Pragma("unroll") for (int k = 0; k < 2; ++k) dst[m][k] = *(const LAS bf16x8*)(lds + G8_SA(b, h) + aoff + m * 2048 + k * 1024); } while (0)
; #define G8_LDB(dst, b, h) do { _Pragma("unroll") for (int n = 0; n < 2; ++n) _Pragma("unroll") for (int k = 0; k < 2; ++k) dst[n][k] = *(const LAS bf16x8*)(lds + G8_SB(b, h) + boff + n * 2048 + k * 1024); } while (0)
; #define G8_MMA(ai, bj, At, Bt) do { __builtin_amdgcn_s_setprio(1); _Pragma("unroll") for (int m = 0; m < 4; ++m) _Pragma("unroll") for (int n = 0; n < 2; ++n) _Pragma("unroll") for (int k = 0; k < 2; ++k) \
;         acc[ai][bj][m][n] = __builtin_amdgcn_mfma_f32_16x16x32_bf16(Bt[n][k], At[m][k], acc[ai][bj][m][n], 0, 0, 0); __builtin_amdgcn_s_setprio(0); } while (0)
; #define G8_WAIT_V(n) asm volatile("s_waitcnt vmcnt(" #n ")" ::: "memory")
; #define G8_WAIT_L(n) asm volatile("s_waitcnt lgkmcnt(" #n ")" ::: "memory")
; template <class Epi, class Sched>
; __device__ __forceinline__ void gemm_phase(int wv, LAS unsigned char* lds, const int K, const Sched& S, const Epi& E) {
;     ...
;         for (int t = 0; t < nt; t += 2) {
;             const bool last = (t == nt - 2);
;             const char* a1 = cA + (size_t)(t + 1) * kstep;
;             const char* a2 = last ? nA : cA + (size_t)(t + 2) * kstep; const char* b2 = last ? nB : cB + (size_t)(t + 2) * kstep;
;             const char* a3 = a2 + kstep; const char* b3 = b2 + kstep;
;             G8_LDB(B0, 0, 0); G8_SCHED; G8_LDA(At, 0, 0); G8_STAGE(G8_SA(1, 1), a1 + hstep, voffA);
;             G8_WAIT_L(8); G8_BAR; G8_WAIT_L(0); G8_MMA(0, 0, At, B0); G8_BAR; G8_SCHED;
;             G8_LDB(B1, 0, 1); G8_STAGE(G8_SB(0, 0), b2, voffB);
;             G8_BAR; G8_WAIT_L(0); G8_MMA(0, 1, At, B1); G8_BAR;
;             if (full) G8_LDA(At, 0, 1); G8_STAGE(G8_SA(0, 0), a2, voffA);
;             G8_BAR; G8_WAIT_L(0); if (full) G8_MMA(1, 0, At, B0); G8_BAR; G8_SCHED;
;             G8_STAGE(G8_SB(0, 1), b2 + hstep, voffB);
;             G8_WAIT_V(6); G8_BAR; if (full) G8_MMA(1, 1, At, B1); G8_BAR;
.LBB0_1092:
	s_add_i32 s53, s40, 2
	s_add_u32 s41, s38, 0xfffc0080
	s_addc_u32 s42, s39, -1
	s_add_i32 s60, 0, 0x10000
	v_add_u32_e32 v0, s60, v216
	ds_read_b128 v[106:109], v0
	ds_read_b128 v[110:113], v0 offset:1024
	ds_read_b128 v[114:117], v0 offset:2048
	ds_read_b128 v[118:121], v0 offset:3072
	s_cmp_eq_u32 s50, s40
	s_cselect_b32 s40, s49, s51
	s_cselect_b32 s43, s4, s42
	s_cselect_b32 s42, s5, s41
	s_cselect_b32 s41, s48, s52
	v_lshl_add_u64 v[190:191], s[38:39], 0, v[186:187]
	s_add_i32 m0, s63, 0xc000
	ds_read_b128 v[146:149], v217
	ds_read_b128 v[150:153], v217 offset:1024
	ds_read_b128 v[154:157], v217 offset:2048
	ds_read_b128 v[158:161], v217 offset:3072
	ds_read_b128 v[162:165], v217 offset:4096
	ds_read_b128 v[166:169], v217 offset:5120
	ds_read_b128 v[170:173], v217 offset:6144
	ds_read_b128 v[174:177], v217 offset:7168
	global_load_lds_dwordx4 v[190:191], off
	v_lshl_add_u64 v[190:191], s[38:39], 0, v[188:189]
	s_add_i32 m0, s63, 0xe000
	s_nop 0
	global_load_lds_dwordx4 v[190:191], off
	s_waitcnt lgkmcnt(8)
	s_barrier
	s_waitcnt lgkmcnt(0)
	s_waitcnt lgkmcnt(0)
	v_mfma_f32_16x16x32_bf16 v[142:145], v[106:109], v[146:149], v[142:145]
	v_mfma_f32_16x16x32_bf16 v[138:141], v[114:117], v[146:149], v[138:141]
	v_mfma_f32_16x16x32_bf16 v[126:129], v[106:109], v[154:157], v[126:129]
	v_mfma_f32_16x16x32_bf16 v[122:125], v[114:117], v[154:157], v[122:125]
	v_mfma_f32_16x16x32_bf16 v[94:97], v[106:109], v[162:165], v[94:97]
	v_mfma_f32_16x16x32_bf16 v[90:93], v[114:117], v[162:165], v[90:93]
	v_mfma_f32_16x16x32_bf16 v[78:81], v[106:109], v[170:173], v[78:81]
	v_mfma_f32_16x16x32_bf16 v[74:77], v[114:117], v[170:173], v[74:77]
	v_mfma_f32_16x16x32_bf16 v[142:145], v[110:113], v[150:153], v[142:145]
	v_mfma_f32_16x16x32_bf16 v[138:141], v[118:121], v[150:153], v[138:141]
	v_mfma_f32_16x16x32_bf16 v[126:129], v[110:113], v[158:161], v[126:129]
	v_mfma_f32_16x16x32_bf16 v[122:125], v[118:121], v[158:161], v[122:125]
	v_mfma_f32_16x16x32_bf16 v[94:97], v[110:113], v[166:169], v[94:97]
	v_mfma_f32_16x16x32_bf16 v[90:93], v[118:121], v[166:169], v[90:93]
	v_mfma_f32_16x16x32_bf16 v[78:81], v[110:113], v[174:177], v[78:81]
	v_mfma_f32_16x16x32_bf16 v[74:77], v[118:121], v[174:177], v[74:77]
	s_barrier
	s_add_i32 s64, 0, 0x14000
	s_add_i32 s60, s60, s3
	v_add_u32_e32 v0, s64, v216
	v_lshl_add_u64 v[194:195], s[40:41], 0, v[180:181]
	s_mov_b32 m0, s60
	ds_read_b128 v[190:193], v0
	ds_read_b128 v[198:201], v0 offset:1024
	ds_read_b128 v[206:209], v0 offset:2048
	ds_read_b128 v[210:213], v0 offset:3072
	global_load_lds_dwordx4 v[194:195], off
	v_lshl_add_u64 v[204:205], s[40:41], 0, v[184:185]
	s_add_i32 m0, s60, 0x2000
	s_nop 0
	global_load_lds_dwordx4 v[204:205], off
	s_barrier
	s_waitcnt lgkmcnt(3)
	v_mfma_f32_16x16x32_bf16 v[134:137], v[190:193], v[146:149], v[134:137]
	s_waitcnt lgkmcnt(1)
	v_mfma_f32_16x16x32_bf16 v[130:133], v[206:209], v[146:149], v[130:133]
	v_mfma_f32_16x16x32_bf16 v[102:105], v[190:193], v[154:157], v[102:105]
	v_mfma_f32_16x16x32_bf16 v[98:101], v[206:209], v[154:157], v[98:101]
	v_mfma_f32_16x16x32_bf16 v[86:89], v[190:193], v[162:165], v[86:89]
	v_mfma_f32_16x16x32_bf16 v[82:85], v[206:209], v[162:165], v[82:85]
	v_mfma_f32_16x16x32_bf16 v[70:73], v[190:193], v[170:173], v[70:73]
	v_mfma_f32_16x16x32_bf16 v[66:69], v[206:209], v[170:173], v[66:69]
	v_mfma_f32_16x16x32_bf16 v[134:137], v[198:201], v[150:153], v[134:137]
	s_waitcnt lgkmcnt(0)
	v_mfma_f32_16x16x32_bf16 v[130:133], v[210:213], v[150:153], v[130:133]
	v_mfma_f32_16x16x32_bf16 v[102:105], v[198:201], v[158:161], v[102:105]
	v_mfma_f32_16x16x32_bf16 v[98:101], v[210:213], v[158:161], v[98:101]
	v_mfma_f32_16x16x32_bf16 v[86:89], v[198:201], v[166:169], v[86:89]
	v_mfma_f32_16x16x32_bf16 v[82:85], v[210:213], v[166:169], v[82:85]
	v_mfma_f32_16x16x32_bf16 v[70:73], v[198:201], v[174:177], v[70:73]
	v_mfma_f32_16x16x32_bf16 v[66:69], v[210:213], v[174:177], v[66:69]
	s_mov_b32 m0, s63
	v_lshl_add_u64 v[214:215], s[42:43], 0, v[178:179]
	s_barrier
	ds_read_b128 v[146:149], v217 offset:16384
	ds_read_b128 v[150:153], v217 offset:17408
	ds_read_b128 v[154:157], v217 offset:18432
	ds_read_b128 v[158:161], v217 offset:19456
	ds_read_b128 v[162:165], v217 offset:20480
	ds_read_b128 v[166:169], v217 offset:21504
	ds_read_b128 v[170:173], v217 offset:22528
	ds_read_b128 v[174:177], v217 offset:23552
	global_load_lds_dwordx4 v[214:215], off
	v_lshl_add_u64 v[218:219], s[42:43], 0, v[182:183]
	s_mov_b32 m0, s75
	s_nop 0
	global_load_lds_dwordx4 v[218:219], off
	s_barrier
	s_waitcnt lgkmcnt(7)
	v_mfma_f32_16x16x32_bf16 v[62:65], v[106:109], v[146:149], v[62:65]
	v_mfma_f32_16x16x32_bf16 v[58:61], v[114:117], v[146:149], v[58:61]
	s_waitcnt lgkmcnt(5)
	v_mfma_f32_16x16x32_bf16 v[46:49], v[106:109], v[154:157], v[46:49]
	v_mfma_f32_16x16x32_bf16 v[42:45], v[114:117], v[154:157], v[42:45]
	s_waitcnt lgkmcnt(3)
	v_mfma_f32_16x16x32_bf16 v[30:33], v[106:109], v[162:165], v[30:33]
	v_mfma_f32_16x16x32_bf16 v[26:29], v[114:117], v[162:165], v[26:29]
	s_waitcnt lgkmcnt(1)
	v_mfma_f32_16x16x32_bf16 v[18:21], v[106:109], v[170:173], v[18:21]
	v_mfma_f32_16x16x32_bf16 v[10:13], v[114:117], v[170:173], v[10:13]
	v_mfma_f32_16x16x32_bf16 v[62:65], v[110:113], v[150:153], v[62:65]
	v_mfma_f32_16x16x32_bf16 v[58:61], v[118:121], v[150:153], v[58:61]
	v_mfma_f32_16x16x32_bf16 v[46:49], v[110:113], v[158:161], v[46:49]
	v_mfma_f32_16x16x32_bf16 v[42:45], v[118:121], v[158:161], v[42:45]
	v_mfma_f32_16x16x32_bf16 v[30:33], v[110:113], v[166:169], v[30:33]
	v_mfma_f32_16x16x32_bf16 v[26:29], v[118:121], v[166:169], v[26:29]
	s_waitcnt lgkmcnt(0)
	v_mfma_f32_16x16x32_bf16 v[18:21], v[110:113], v[174:177], v[18:21]
	v_mfma_f32_16x16x32_bf16 v[10:13], v[118:121], v[174:177], v[10:13]
	s_barrier
; #define G8_STAGE(bufoff, gbase, voff) do { _Pragma("unroll") for (int _i = 0; _i < 2; ++_i) \
;         __builtin_amdgcn_global_load_lds((const unsigned*)((const char*)(gbase) + (voff)[_i]), (LAS unsigned*)(lds + (bufoff) + ldsw + _i * 8192), 16, 0, 0); } while (0)
; #define G8_LDA(dst, b, h) do { _Pragma("unroll") for (int m = 0; m < 4; ++m) _Pragma("unroll") for (int k = 0; k < 2; ++k) dst[m][k] = *(const LAS bf16x8*)(lds + G8_SA(b, h) + aoff + m * 2048 + k * 1024); } while (0)
; #define G8_LDB(dst, b, h) do { _Pragma("unroll") for (int n = 0; n < 2; ++n) _Pragma("unroll") for (int k = 0; k < 2; ++k) dst[n][k] = *(const LAS bf16x8*)(lds + G8_SB(b, h) + boff + n * 2048 + k * 1024); } while (0)
; #define G8_MMA(ai, bj, At, Bt) do { __builtin_amdgcn_s_setprio(1); _Pragma("unroll") for (int m = 0; m < 4; ++m) _Pragma("unroll") for (int n = 0; n < 2; ++n) _Pragma("unroll") for (int k = 0; k < 2; ++k) \
;         acc[ai][bj][m][n] = __builtin_amdgcn_mfma_f32_16x16x32_bf16(Bt[n][k], At[m][k], acc[ai][bj][m][n], 0, 0, 0); __builtin_amdgcn_s_setprio(0); } while (0)
; #define G8_WAIT_V(n) asm volatile("s_waitcnt vmcnt(" #n ")" ::: "memory")
; #define G8_WAIT_L(n) asm volatile("s_waitcnt lgkmcnt(" #n ")" ::: "memory")
; #define G8_BAR __builtin_amdgcn_s_barrier()
; #define G8_SCHED __builtin_amdgcn_sched_barrier(0)
; template <class Epi, class Sched>
; __device__ __forceinline__ void gemm_phase(int wv, LAS unsigned char* lds, const int K, const Sched& S, const Epi& E) {
;     ...
;             G8_STAGE(G8_SB(0, 1), b2 + hstep, voffB);
;             G8_WAIT_V(6); G8_BAR; if (full) G8_MMA(1, 1, At, B1); G8_BAR;
;             G8_LDB(B0, 1, 0); G8_SCHED; G8_LDA(At, 1, 0); G8_STAGE(G8_SA(0, 1), a2 + hstep, voffA);
;             G8_WAIT_L(8); G8_BAR; G8_WAIT_L(0); G8_MMA(0, 0, At, B0); G8_BAR; G8_SCHED;
;             G8_LDB(B1, 1, 1); G8_STAGE(G8_SB(1, 0), b3, voffB);
;             G8_BAR; G8_WAIT_L(0); G8_MMA(0, 1, At, B1); G8_BAR;
;             if (full) G8_LDA(At, 1, 1); G8_STAGE(G8_SA(1, 0), a3, voffA);
;             G8_BAR; G8_WAIT_L(0); if (full) G8_MMA(1, 0, At, B0); G8_BAR; G8_SCHED;
	s_add_u32 s60, s40, 0x40000
	s_addc_u32 s61, s41, 0
	s_add_i32 s64, s64, s3
	v_lshl_add_u64 v[106:107], s[60:61], 0, v[180:181]
	s_mov_b32 m0, s64
	s_nop 0
	global_load_lds_dwordx4 v[106:107], off
	v_lshl_add_u64 v[106:107], s[60:61], 0, v[184:185]
	s_add_i32 m0, s64, 0x2000
	s_nop 0
	global_load_lds_dwordx4 v[106:107], off
	s_waitcnt vmcnt(6)
	s_barrier
	v_mfma_f32_16x16x32_bf16 v[54:57], v[190:193], v[146:149], v[54:57]
	v_mfma_f32_16x16x32_bf16 v[50:53], v[206:209], v[146:149], v[50:53]
	v_mfma_f32_16x16x32_bf16 v[38:41], v[190:193], v[154:157], v[38:41]
	v_mfma_f32_16x16x32_bf16 v[34:37], v[206:209], v[154:157], v[34:37]
	v_mfma_f32_16x16x32_bf16 v[22:25], v[190:193], v[162:165], v[22:25]
	v_mfma_f32_16x16x32_bf16 v[14:17], v[206:209], v[162:165], v[14:17]
	v_mfma_f32_16x16x32_bf16 v[6:9], v[190:193], v[170:173], v[6:9]
	v_mfma_f32_16x16x32_bf16 v[2:5], v[206:209], v[170:173], v[2:5]
	v_mfma_f32_16x16x32_bf16 v[54:57], v[198:201], v[150:153], v[54:57]
	v_mfma_f32_16x16x32_bf16 v[50:53], v[210:213], v[150:153], v[50:53]
	v_mfma_f32_16x16x32_bf16 v[38:41], v[198:201], v[158:161], v[38:41]
	v_mfma_f32_16x16x32_bf16 v[34:37], v[210:213], v[158:161], v[34:37]
	v_mfma_f32_16x16x32_bf16 v[22:25], v[198:201], v[166:169], v[22:25]
	v_mfma_f32_16x16x32_bf16 v[14:17], v[210:213], v[166:169], v[14:17]
	v_mfma_f32_16x16x32_bf16 v[6:9], v[198:201], v[174:177], v[6:9]
	v_mfma_f32_16x16x32_bf16 v[2:5], v[210:213], v[174:177], v[2:5]
	s_add_i32 s60, 0, 0x18000
	v_add_u32_e32 v0, s60, v216
	s_barrier
	ds_read_b128 v[106:109], v0
	ds_read_b128 v[110:113], v0 offset:1024
	ds_read_b128 v[114:117], v0 offset:2048
	ds_read_b128 v[118:121], v0 offset:3072
	s_add_u32 s42, s42, 0x40000
	s_addc_u32 s43, s43, 0
	s_mov_b32 m0, s78
	v_lshl_add_u64 v[190:191], s[42:43], 0, v[178:179]
	ds_read_b128 v[146:149], v217 offset:32768
	ds_read_b128 v[150:153], v217 offset:33792
	ds_read_b128 v[154:157], v217 offset:34816
	ds_read_b128 v[158:161], v217 offset:35840
	ds_read_b128 v[162:165], v217 offset:36864
	ds_read_b128 v[166:169], v217 offset:37888
	ds_read_b128 v[170:173], v217 offset:38912
	ds_read_b128 v[174:177], v217 offset:39936
	global_load_lds_dwordx4 v[190:191], off
	v_lshl_add_u64 v[190:191], s[42:43], 0, v[182:183]
	s_mov_b32 m0, s79
	s_nop 0
	global_load_lds_dwordx4 v[190:191], off
	s_waitcnt lgkmcnt(8)
	s_barrier
	s_waitcnt lgkmcnt(7)
	v_mfma_f32_16x16x32_bf16 v[142:145], v[106:109], v[146:149], v[142:145]
	v_mfma_f32_16x16x32_bf16 v[138:141], v[114:117], v[146:149], v[138:141]
	s_waitcnt lgkmcnt(5)
	v_mfma_f32_16x16x32_bf16 v[126:129], v[106:109], v[154:157], v[126:129]
	v_mfma_f32_16x16x32_bf16 v[122:125], v[114:117], v[154:157], v[122:125]
	s_waitcnt lgkmcnt(3)
	v_mfma_f32_16x16x32_bf16 v[94:97], v[106:109], v[162:165], v[94:97]
	v_mfma_f32_16x16x32_bf16 v[90:93], v[114:117], v[162:165], v[90:93]
	s_waitcnt lgkmcnt(1)
	v_mfma_f32_16x16x32_bf16 v[78:81], v[106:109], v[170:173], v[78:81]
	v_mfma_f32_16x16x32_bf16 v[74:77], v[114:117], v[170:173], v[74:77]
	v_mfma_f32_16x16x32_bf16 v[142:145], v[110:113], v[150:153], v[142:145]
	v_mfma_f32_16x16x32_bf16 v[138:141], v[118:121], v[150:153], v[138:141]
	v_mfma_f32_16x16x32_bf16 v[126:129], v[110:113], v[158:161], v[126:129]
	v_mfma_f32_16x16x32_bf16 v[122:125], v[118:121], v[158:161], v[122:125]
	v_mfma_f32_16x16x32_bf16 v[94:97], v[110:113], v[166:169], v[94:97]
	v_mfma_f32_16x16x32_bf16 v[90:93], v[118:121], v[166:169], v[90:93]
	s_waitcnt lgkmcnt(0)
	v_mfma_f32_16x16x32_bf16 v[78:81], v[110:113], v[174:177], v[78:81]
	v_mfma_f32_16x16x32_bf16 v[74:77], v[118:121], v[174:177], v[74:77]
	s_barrier
	s_add_i32 s42, 0, 0x1c000
	s_add_i32 s43, s60, s3
	v_add_u32_e32 v0, s42, v216
	v_lshl_add_u64 v[194:195], v[194:195], 0, s[58:59]
	s_mov_b32 m0, s43
	ds_read_b128 v[190:193], v0
	ds_read_b128 v[198:201], v0 offset:1024
	ds_read_b128 v[206:209], v0 offset:2048
	ds_read_b128 v[210:213], v0 offset:3072
	global_load_lds_dwordx4 v[194:195], off
	v_lshl_add_u64 v[194:195], v[204:205], 0, s[58:59]
	s_add_i32 m0, s43, 0x2000
	s_nop 0
	global_load_lds_dwordx4 v[194:195], off
	s_barrier
	s_waitcnt lgkmcnt(3)
	v_mfma_f32_16x16x32_bf16 v[134:137], v[190:193], v[146:149], v[134:137]
	s_waitcnt lgkmcnt(1)
	v_mfma_f32_16x16x32_bf16 v[130:133], v[206:209], v[146:149], v[130:133]
	v_mfma_f32_16x16x32_bf16 v[102:105], v[190:193], v[154:157], v[102:105]
	v_mfma_f32_16x16x32_bf16 v[98:101], v[206:209], v[154:157], v[98:101]
	v_mfma_f32_16x16x32_bf16 v[86:89], v[190:193], v[162:165], v[86:89]
	v_mfma_f32_16x16x32_bf16 v[82:85], v[206:209], v[162:165], v[82:85]
	v_mfma_f32_16x16x32_bf16 v[70:73], v[190:193], v[170:173], v[70:73]
	v_mfma_f32_16x16x32_bf16 v[66:69], v[206:209], v[170:173], v[66:69]
	v_mfma_f32_16x16x32_bf16 v[134:137], v[198:201], v[150:153], v[134:137]
	s_waitcnt lgkmcnt(0)
	v_mfma_f32_16x16x32_bf16 v[130:133], v[210:213], v[150:153], v[130:133]
	v_mfma_f32_16x16x32_bf16 v[102:105], v[198:201], v[158:161], v[102:105]
	v_mfma_f32_16x16x32_bf16 v[98:101], v[210:213], v[158:161], v[98:101]
	v_mfma_f32_16x16x32_bf16 v[86:89], v[198:201], v[166:169], v[86:89]
	v_mfma_f32_16x16x32_bf16 v[82:85], v[210:213], v[166:169], v[82:85]
	v_mfma_f32_16x16x32_bf16 v[70:73], v[198:201], v[174:177], v[70:73]
	v_mfma_f32_16x16x32_bf16 v[66:69], v[210:213], v[174:177], v[66:69]
	s_mov_b32 m0, s86
	v_lshl_add_u64 v[194:195], v[214:215], 0, s[58:59]
	s_barrier
	ds_read_b128 v[146:149], v217 offset:49152
	ds_read_b128 v[150:153], v217 offset:50176
	ds_read_b128 v[154:157], v217 offset:51200
	ds_read_b128 v[158:161], v217 offset:52224
	ds_read_b128 v[162:165], v217 offset:53248
	ds_read_b128 v[166:169], v217 offset:54272
	ds_read_b128 v[170:173], v217 offset:55296
	ds_read_b128 v[174:177], v217 offset:56320
	global_load_lds_dwordx4 v[194:195], off
	v_lshl_add_u64 v[194:195], v[218:219], 0, s[58:59]
	s_mov_b32 m0, s87
	s_nop 0
	global_load_lds_dwordx4 v[194:195], off
	s_barrier
; __device__ __forceinline__ int otid(int wv) { int ln; asm volatile("v_mbcnt_lo_u32_b32 %0, -1, 0\n\tv_mbcnt_hi_u32_b32 %0, -1, %0" : "=v"(ln)); return wv * 64 + ln; }
; #define G8_STAGE(bufoff, gbase, voff) do { _Pragma("unroll") for (int _i = 0; _i < 2; ++_i) \
;         __builtin_amdgcn_global_load_lds((const unsigned*)((const char*)(gbase) + (voff)[_i]), (LAS unsigned*)(lds + (bufoff) + ldsw + _i * 8192), 16, 0, 0); } while (0)
; #define G8_MMA(ai, bj, At, Bt) do { __builtin_amdgcn_s_setprio(1); _Pragma("unroll") for (int m = 0; m < 4; ++m) _Pragma("unroll") for (int n = 0; n < 2; ++n) _Pragma("unroll") for (int k = 0; k < 2; ++k) \
;         acc[ai][bj][m][n] = __builtin_amdgcn_mfma_f32_16x16x32_bf16(Bt[n][k], At[m][k], acc[ai][bj][m][n], 0, 0, 0); __builtin_amdgcn_s_setprio(0); } while (0)
; #define G8_WAIT_V(n) asm volatile("s_waitcnt vmcnt(" #n ")" ::: "memory")
; #define G8_WAIT_L(n) asm volatile("s_waitcnt lgkmcnt(" #n ")" ::: "memory")
; #define G8_BAR __builtin_amdgcn_s_barrier()
; #define G8_SCHED __builtin_amdgcn_sched_barrier(0)
; template <class Epi, class Sched>
; __device__ __forceinline__ void gemm_phase(int wv, LAS unsigned char* lds, const int K, const Sched& S, const Epi& E) {
;     ...
;             G8_BAR; G8_WAIT_L(0); if (full) G8_MMA(1, 0, At, B0); G8_BAR; G8_SCHED;
;             G8_STAGE(G8_SB(1, 1), b3 + hstep, voffB);
;             G8_WAIT_V(6); G8_BAR; if (full) G8_MMA(1, 1, At, B1); G8_BAR;
;         }
;         { const int t2 = otid(wv); E(acc, cur, wr, wc, t2 & 15, (t2 >> 4) & 3); }
;         if (!has_next) break;
	s_waitcnt lgkmcnt(7)
	v_mfma_f32_16x16x32_bf16 v[62:65], v[106:109], v[146:149], v[62:65]
	v_mfma_f32_16x16x32_bf16 v[58:61], v[114:117], v[146:149], v[58:61]
	s_waitcnt lgkmcnt(5)
	v_mfma_f32_16x16x32_bf16 v[46:49], v[106:109], v[154:157], v[46:49]
	v_mfma_f32_16x16x32_bf16 v[42:45], v[114:117], v[154:157], v[42:45]
	s_waitcnt lgkmcnt(3)
	v_mfma_f32_16x16x32_bf16 v[30:33], v[106:109], v[162:165], v[30:33]
	v_mfma_f32_16x16x32_bf16 v[26:29], v[114:117], v[162:165], v[26:29]
	s_waitcnt lgkmcnt(1)
	v_mfma_f32_16x16x32_bf16 v[18:21], v[106:109], v[170:173], v[18:21]
	v_mfma_f32_16x16x32_bf16 v[10:13], v[114:117], v[170:173], v[10:13]
	v_mfma_f32_16x16x32_bf16 v[62:65], v[110:113], v[150:153], v[62:65]
	v_mfma_f32_16x16x32_bf16 v[58:61], v[118:121], v[150:153], v[58:61]
	v_mfma_f32_16x16x32_bf16 v[46:49], v[110:113], v[158:161], v[46:49]
	v_mfma_f32_16x16x32_bf16 v[42:45], v[118:121], v[158:161], v[42:45]
	v_mfma_f32_16x16x32_bf16 v[30:33], v[110:113], v[166:169], v[30:33]
	v_mfma_f32_16x16x32_bf16 v[26:29], v[118:121], v[166:169], v[26:29]
	s_waitcnt lgkmcnt(0)
	v_mfma_f32_16x16x32_bf16 v[18:21], v[110:113], v[174:177], v[18:21]
	v_mfma_f32_16x16x32_bf16 v[10:13], v[118:121], v[174:177], v[10:13]
	s_barrier
	s_add_u32 s40, s40, 0x40080
	s_addc_u32 s41, s41, 0
	s_add_i32 s42, s42, s3
	v_lshl_add_u64 v[106:107], s[40:41], 0, v[180:181]
	s_mov_b32 m0, s42
	s_nop 0
	global_load_lds_dwordx4 v[106:107], off
	v_lshl_add_u64 v[106:107], s[40:41], 0, v[184:185]
	s_add_i32 m0, s42, 0x2000
	s_nop 0
	global_load_lds_dwordx4 v[106:107], off
	s_waitcnt vmcnt(6)
	s_barrier
	v_mfma_f32_16x16x32_bf16 v[54:57], v[190:193], v[146:149], v[54:57]
	v_mfma_f32_16x16x32_bf16 v[50:53], v[206:209], v[146:149], v[50:53]
	v_mfma_f32_16x16x32_bf16 v[38:41], v[190:193], v[154:157], v[38:41]
	v_mfma_f32_16x16x32_bf16 v[34:37], v[206:209], v[154:157], v[34:37]
	v_mfma_f32_16x16x32_bf16 v[22:25], v[190:193], v[162:165], v[22:25]
	v_mfma_f32_16x16x32_bf16 v[14:17], v[206:209], v[162:165], v[14:17]
	v_mfma_f32_16x16x32_bf16 v[6:9], v[190:193], v[170:173], v[6:9]
	v_mfma_f32_16x16x32_bf16 v[2:5], v[206:209], v[170:173], v[2:5]
	v_mfma_f32_16x16x32_bf16 v[54:57], v[198:201], v[150:153], v[54:57]
	v_mfma_f32_16x16x32_bf16 v[50:53], v[210:213], v[150:153], v[50:53]
	v_mfma_f32_16x16x32_bf16 v[38:41], v[198:201], v[158:161], v[38:41]
	v_mfma_f32_16x16x32_bf16 v[34:37], v[210:213], v[158:161], v[34:37]
	v_mfma_f32_16x16x32_bf16 v[22:25], v[198:201], v[166:169], v[22:25]
	v_mfma_f32_16x16x32_bf16 v[14:17], v[210:213], v[166:169], v[14:17]
	v_mfma_f32_16x16x32_bf16 v[6:9], v[198:201], v[174:177], v[6:9]
	v_mfma_f32_16x16x32_bf16 v[2:5], v[210:213], v[174:177], v[2:5]
	s_add_u32 s38, s38, 0x100
	s_addc_u32 s39, s39, 0
	s_add_u32 s51, s51, 0x100
	s_addc_u32 s52, s52, 0
	s_cmp_ge_i32 s53, s96
	s_mov_b32 s40, s53
	s_barrier
	s_cbranch_scc0 .LBB0_1092
	v_mbcnt_lo_u32_b32 v0, -1, 0
	v_mbcnt_hi_u32_b32 v0, -1, v0
	s_cmp_eq_u32 s95, 0
	v_and_or_b32 v190, v0, 15, s82
	v_lshrrev_b32_e32 v0, 1, v0
	v_and_or_b32 v218, v0, 24, s84
	v_or_b32_e32 v146, 16, v190
	v_or_b32_e32 v194, 32, v190
	v_or_b32_e32 v192, 48, v190
	v_ashrrev_i32_e32 v191, 31, v190
	v_lshlrev_b32_e32 v206, 1, v218
	v_ashrrev_i32_e32 v147, 31, v146
	v_ashrrev_i32_e32 v195, 31, v194
	v_ashrrev_i32_e32 v193, 31, v192
	s_cbranch_scc1 .LBB0_1095
; __device__ __forceinline__ unsigned pk_bf16(float lo, float hi) { unsigned r; asm volatile("v_cvt_pk_bf16_f32 %0, %1, %2" : "=v"(r) : "v"(lo), "v"(hi)); return r; }
;     __device__ __forceinline__ void operator()(const f32x4 (&acc)[2][2][4][2], const Unit& u, int wr, int wc, int fr, int fq) const {
;     ...
;             for (int ai = 0; ai < 2; ++ai)
; #pragma unroll
;                 for (int m = 0; m < 4; ++m) { bf16_t* op = (bf16_t*)u.o + (size_t)(row0 + ai * HALF + m * 16) * 1024 + col0;
; #pragma unroll
;                     for (int bj = 0; bj < 2; ++bj) { const f32x4 v0 = acc[ai][bj][m][0], v1 = acc[ai][bj][m][1];
;                         u32x4 w; w.x = pk_bf16(v0[0], v0[1]); w.y = pk_bf16(v0[2], v0[3]); w.z = pk_bf16(v1[0], v1[1]); w.w = pk_bf16(v1[2], v1[3]); st16_wt(op + bj * HALF, w); } }
	v_lshlrev_b64 v[106:107], 11, v[190:191]
	v_lshl_add_u64 v[106:107], s[16:17], 0, v[106:107]
	v_mov_b32_e32 v207, v1
	v_lshl_add_u64 v[106:107], v[106:107], 0, v[206:207]
	v_cvt_pk_bf16_f32 v108, v142, v143
	v_cvt_pk_bf16_f32 v109, v144, v145
	v_cvt_pk_bf16_f32 v110, v138, v139
	v_cvt_pk_bf16_f32 v111, v140, v141
	global_store_dwordx4 v[106:107], v[108:111], off
	s_mov_b64 s[4:5], 0x40000
	s_nop 0
	v_cvt_pk_bf16_f32 v108, v134, v135
	v_cvt_pk_bf16_f32 v109, v136, v137
	v_cvt_pk_bf16_f32 v110, v130, v131
	v_cvt_pk_bf16_f32 v111, v132, v133
	global_store_dwordx4 v[106:107], v[108:111], off offset:256
	s_nop 1
	v_lshlrev_b64 v[108:109], 11, v[146:147]
	v_lshl_add_u64 v[108:109], s[16:17], 0, v[108:109]
	v_lshl_add_u64 v[112:113], v[108:109], 0, v[206:207]
	v_cvt_pk_bf16_f32 v108, v126, v127
	v_cvt_pk_bf16_f32 v109, v128, v129
	v_cvt_pk_bf16_f32 v110, v122, v123
	v_cvt_pk_bf16_f32 v111, v124, v125
	global_store_dwordx4 v[112:113], v[108:111], off
	s_nop 1
	v_cvt_pk_bf16_f32 v108, v102, v103
	v_cvt_pk_bf16_f32 v109, v104, v105
	v_cvt_pk_bf16_f32 v110, v98, v99
	v_cvt_pk_bf16_f32 v111, v100, v101
	global_store_dwordx4 v[112:113], v[108:111], off offset:256
	s_nop 1
	v_lshlrev_b64 v[108:109], 11, v[194:195]
	v_lshl_add_u64 v[108:109], s[16:17], 0, v[108:109]
	v_lshl_add_u64 v[112:113], v[108:109], 0, v[206:207]
	v_cvt_pk_bf16_f32 v108, v94, v95
	v_cvt_pk_bf16_f32 v109, v96, v97
	v_cvt_pk_bf16_f32 v110, v90, v91
	v_cvt_pk_bf16_f32 v111, v92, v93
	global_store_dwordx4 v[112:113], v[108:111], off
	s_nop 1
	v_cvt_pk_bf16_f32 v108, v86, v87
	v_cvt_pk_bf16_f32 v109, v88, v89
	v_cvt_pk_bf16_f32 v110, v82, v83
	v_cvt_pk_bf16_f32 v111, v84, v85
	global_store_dwordx4 v[112:113], v[108:111], off offset:256
	s_nop 1
	v_lshlrev_b64 v[108:109], 11, v[192:193]
	v_lshl_add_u64 v[108:109], s[16:17], 0, v[108:109]
	v_lshl_add_u64 v[112:113], v[108:109], 0, v[206:207]
	v_cvt_pk_bf16_f32 v108, v78, v79
	v_cvt_pk_bf16_f32 v109, v80, v81
	v_cvt_pk_bf16_f32 v110, v74, v75
	v_cvt_pk_bf16_f32 v111, v76, v77
	global_store_dwordx4 v[112:113], v[108:111], off
	s_nop 1
	v_cvt_pk_bf16_f32 v108, v70, v71
	v_cvt_pk_bf16_f32 v109, v72, v73
	v_cvt_pk_bf16_f32 v110, v66, v67
	v_cvt_pk_bf16_f32 v111, v68, v69
	global_store_dwordx4 v[112:113], v[108:111], off offset:256
	v_lshl_add_u64 v[112:113], v[106:107], 0, s[4:5]
	s_mov_b32 s4, 0x40000
	v_add_co_u32_e32 v114, vcc, s4, v106
	v_cvt_pk_bf16_f32 v108, v62, v63
	v_cvt_pk_bf16_f32 v109, v64, v65
	v_cvt_pk_bf16_f32 v110, v58, v59
	v_cvt_pk_bf16_f32 v111, v60, v61
	s_nop 1
	v_addc_co_u32_e32 v115, vcc, 0, v107, vcc
	s_mov_b64 s[4:5], 0x48000
	global_store_dwordx4 v[114:115], v[108:111], off
	s_nop 1
	v_cvt_pk_bf16_f32 v108, v54, v55
	v_cvt_pk_bf16_f32 v109, v56, v57
	v_cvt_pk_bf16_f32 v110, v50, v51
	v_cvt_pk_bf16_f32 v111, v52, v53
	global_store_dwordx4 v[112:113], v[108:111], off offset:256
	v_lshl_add_u64 v[112:113], v[106:107], 0, s[4:5]
	s_mov_b32 s4, 0x48000
	v_add_co_u32_e32 v114, vcc, s4, v106
	v_cvt_pk_bf16_f32 v108, v46, v47
	v_cvt_pk_bf16_f32 v109, v48, v49
	v_cvt_pk_bf16_f32 v110, v42, v43
	v_cvt_pk_bf16_f32 v111, v44, v45
	s_nop 1
	v_addc_co_u32_e32 v115, vcc, 0, v107, vcc
	s_mov_b64 s[4:5], 0x50000
	global_store_dwordx4 v[114:115], v[108:111], off
	s_nop 1
	v_cvt_pk_bf16_f32 v108, v38, v39
	v_cvt_pk_bf16_f32 v109, v40, v41
	v_cvt_pk_bf16_f32 v110, v34, v35
	v_cvt_pk_bf16_f32 v111, v36, v37
	global_store_dwordx4 v[112:113], v[108:111], off offset:256
	v_lshl_add_u64 v[112:113], v[106:107], 0, s[4:5]
	s_mov_b32 s4, 0x50000
	v_add_co_u32_e32 v114, vcc, s4, v106
	v_cvt_pk_bf16_f32 v108, v30, v31
	v_cvt_pk_bf16_f32 v109, v32, v33
	v_cvt_pk_bf16_f32 v110, v26, v27
	v_cvt_pk_bf16_f32 v111, v28, v29
	s_nop 1
	v_addc_co_u32_e32 v115, vcc, 0, v107, vcc
	s_mov_b64 s[4:5], 0x58000
	global_store_dwordx4 v[114:115], v[108:111], off
	s_nop 1
	v_cvt_pk_bf16_f32 v108, v22, v23
	v_cvt_pk_bf16_f32 v109, v24, v25
	v_cvt_pk_bf16_f32 v110, v14, v15
	v_cvt_pk_bf16_f32 v111, v16, v17
	global_store_dwordx4 v[112:113], v[108:111], off offset:256
	v_lshl_add_u64 v[112:113], v[106:107], 0, s[4:5]
	s_mov_b32 s4, 0x58000
	v_add_co_u32_e32 v106, vcc, s4, v106
	v_cvt_pk_bf16_f32 v108, v18, v19
	v_cvt_pk_bf16_f32 v109, v20, v21
	s_nop 1
	v_addc_co_u32_e32 v107, vcc, 0, v107, vcc
	v_cvt_pk_bf16_f32 v110, v10, v11
	v_cvt_pk_bf16_f32 v111, v12, v13
	global_store_dwordx4 v[106:107], v[108:111], off
	v_cvt_pk_bf16_f32 v106, v6, v7
	v_cvt_pk_bf16_f32 v107, v8, v9
	s_nop 1
	v_cvt_pk_bf16_f32 v108, v2, v3
	v_cvt_pk_bf16_f32 v109, v4, v5
	global_store_dwordx4 v[112:113], v[106:109], off offset:256
	s_cbranch_execnz .LBB0_1078
	s_branch .LBB0_1096

; #define G8_STAGE(bufoff, gbase, voff) do { _Pragma("unroll") for (int _i = 0; _i < 2; ++_i) \
;         __builtin_amdgcn_global_load_lds((const unsigned*)((const char*)(gbase) + (voff)[_i]), (LAS unsigned*)(lds + (bufoff) + ldsw + _i * 8192), 16, 0, 0); } while (0)
; #define G8_LDA(dst, b, h) do { _Pragma("unroll") for (int m = 0; m < 4; ++m) _Pragma("unroll") for (int k = 0; k < 2; ++k) dst[m][k] = *(const LAS bf16x8*)(lds + G8_SA(b, h) + aoff + m * 2048 + k * 1024); } while (0)
; #define G8_LDB(dst, b, h) do { _Pragma("unroll") for (int n = 0; n < 2; ++n) _Pragma("unroll") for (int k = 0; k < 2; ++k) dst[n][k] = *(const LAS bf16x8*)(lds + G8_SB(b, h) + boff + n * 2048 + k * 1024); } while (0)
; #define G8_MMA(ai, bj, At, Bt) do { __builtin_amdgcn_s_setprio(1); _Pragma("unroll") for (int m = 0; m < 4; ++m) _Pragma("unroll") for (int n = 0; n < 2; ++n) _Pragma("unroll") for (int k = 0; k < 2; ++k) \
;         acc[ai][bj][m][n] = __builtin_amdgcn_mfma_f32_16x16x32_bf16(Bt[n][k], At[m][k], acc[ai][bj][m][n], 0, 0, 0); __builtin_amdgcn_s_setprio(0); } while (0)
; #define G8_WAIT_V(n) asm volatile("s_waitcnt vmcnt(" #n ")" ::: "memory")
; #define G8_WAIT_L(n) asm volatile("s_waitcnt lgkmcnt(" #n ")" ::: "memory")
; #define G8_BAR __builtin_amdgcn_s_barrier()
; template <class Epi, class Sched>
; __device__ __forceinline__ void gemm_phase(int wv, LAS unsigned char* lds, const int K, const Sched& S, const Epi& E) {
;     ...
;             const bool last = (t == nt - 2);
;             const char* a1 = cA + (size_t)(t + 1) * kstep;
;             const char* a2 = last ? nA : cA + (size_t)(t + 2) * kstep; const char* b2 = last ? nB : cB + (size_t)(t + 2) * kstep;
;             const char* a3 = a2 + kstep; const char* b3 = b2 + kstep;
;             G8_LDB(B0, 0, 0); G8_SCHED; G8_LDA(At, 0, 0); G8_STAGE(G8_SA(1, 1), a1 + hstep, voffA);
;             G8_WAIT_L(8); G8_BAR; G8_WAIT_L(0); G8_MMA(0, 0, At, B0); G8_BAR; G8_SCHED;
;             G8_LDB(B1, 0, 1); G8_STAGE(G8_SB(0, 0), b2, voffB);
;             G8_BAR; G8_WAIT_L(0); G8_MMA(0, 1, At, B1); G8_BAR;
;             if (full) G8_LDA(At, 0, 1); G8_STAGE(G8_SA(0, 0), a2, voffA);
;             G8_BAR; G8_WAIT_L(0); if (full) G8_MMA(1, 0, At, B0); G8_BAR; G8_SCHED;
;             G8_STAGE(G8_SB(0, 1), b2 + hstep, voffB);
;             G8_WAIT_V(6); G8_BAR; if (full) G8_MMA(1, 1, At, B1); G8_BAR;
.LBB0_1317:
	s_add_i32 s76, 0, 0x10000
	v_add_u32_e32 v0, s76, v220
	ds_read_b128 v[180:183], v0
	ds_read_b128 v[184:187], v0 offset:1024
	ds_read_b128 v[188:191], v0 offset:2048
	ds_read_b128 v[192:195], v0 offset:3072
	s_cmp_eq_u32 s75, 12
	s_cselect_b64 s[40:41], -1, 0
	s_and_b64 s[14:15], s[40:41], exec
	s_cselect_b32 s39, s29, s5
	s_cselect_b32 s38, s28, s4
	v_lshl_add_u64 v[2:3], s[36:37], 0, v[210:211]
	s_add_i32 m0, s42, 0xc000
	s_waitcnt lgkmcnt(0)
	ds_read_b128 v[144:147], v221
	ds_read_b128 v[160:163], v221 offset:1024
	ds_read_b128 v[140:143], v221 offset:2048
	ds_read_b128 v[156:159], v221 offset:3072
	ds_read_b128 v[136:139], v221 offset:4096
	ds_read_b128 v[152:155], v221 offset:5120
	ds_read_b128 v[132:135], v221 offset:6144
	ds_read_b128 v[148:151], v221 offset:7168
	global_load_lds_dwordx4 v[2:3], off
	v_lshl_add_u64 v[2:3], s[36:37], 0, v[212:213]
	s_add_i32 m0, s42, 0xe000
	s_nop 0
	global_load_lds_dwordx4 v[2:3], off
	s_waitcnt lgkmcnt(8)
	s_barrier
	s_waitcnt lgkmcnt(7)
	v_mfma_f32_16x16x32_bf16 v[124:127], v[180:183], v[144:147], v[124:127]
	v_mfma_f32_16x16x32_bf16 v[128:131], v[188:191], v[144:147], v[128:131]
	s_waitcnt lgkmcnt(5)
	v_mfma_f32_16x16x32_bf16 v[108:111], v[180:183], v[140:143], v[108:111]
	v_mfma_f32_16x16x32_bf16 v[112:115], v[188:191], v[140:143], v[112:115]
	s_waitcnt lgkmcnt(3)
	v_mfma_f32_16x16x32_bf16 v[92:95], v[180:183], v[136:139], v[92:95]
	v_mfma_f32_16x16x32_bf16 v[96:99], v[188:191], v[136:139], v[96:99]
	s_waitcnt lgkmcnt(1)
	v_mfma_f32_16x16x32_bf16 v[76:79], v[180:183], v[132:135], v[76:79]
	v_mfma_f32_16x16x32_bf16 v[80:83], v[188:191], v[132:135], v[80:83]
	v_mfma_f32_16x16x32_bf16 v[124:127], v[184:187], v[160:163], v[124:127]
	v_mfma_f32_16x16x32_bf16 v[128:131], v[192:195], v[160:163], v[128:131]
	v_mfma_f32_16x16x32_bf16 v[108:111], v[184:187], v[156:159], v[108:111]
	v_mfma_f32_16x16x32_bf16 v[112:115], v[192:195], v[156:159], v[112:115]
	v_mfma_f32_16x16x32_bf16 v[92:95], v[184:187], v[152:155], v[92:95]
	v_mfma_f32_16x16x32_bf16 v[96:99], v[192:195], v[152:155], v[96:99]
	s_waitcnt lgkmcnt(0)
	v_mfma_f32_16x16x32_bf16 v[76:79], v[184:187], v[148:151], v[76:79]
	v_mfma_f32_16x16x32_bf16 v[80:83], v[192:195], v[148:151], v[80:83]
	s_barrier
	v_add_u32_e32 v0, 0, v220
	v_add_u32_e32 v2, 0x14000, v0
	s_add_i32 s14, s76, s3
	ds_read_b128 v[164:167], v2
	ds_read_b128 v[168:171], v2 offset:1024
	ds_read_b128 v[172:175], v2 offset:2048
	ds_read_b128 v[176:179], v2 offset:3072
	v_lshl_add_u64 v[2:3], s[38:39], 0, v[206:207]
	s_mov_b32 m0, s14
	v_lshl_add_u64 v[214:215], s[38:39], 0, v[208:209]
	global_load_lds_dwordx4 v[2:3], off
	s_add_i32 m0, s14, 0x2000
	s_nop 0
	global_load_lds_dwordx4 v[214:215], off
	s_barrier
	s_waitcnt lgkmcnt(3)
	v_mfma_f32_16x16x32_bf16 v[116:119], v[164:167], v[144:147], v[116:119]
	s_waitcnt lgkmcnt(1)
	v_mfma_f32_16x16x32_bf16 v[120:123], v[172:175], v[144:147], v[120:123]
	v_mfma_f32_16x16x32_bf16 v[100:103], v[164:167], v[140:143], v[100:103]
	v_mfma_f32_16x16x32_bf16 v[104:107], v[172:175], v[140:143], v[104:107]
	v_mfma_f32_16x16x32_bf16 v[84:87], v[164:167], v[136:139], v[84:87]
	v_mfma_f32_16x16x32_bf16 v[88:91], v[172:175], v[136:139], v[88:91]
	v_mfma_f32_16x16x32_bf16 v[72:75], v[164:167], v[132:135], v[72:75]
	v_mfma_f32_16x16x32_bf16 v[68:71], v[172:175], v[132:135], v[68:71]
	v_mfma_f32_16x16x32_bf16 v[116:119], v[168:171], v[160:163], v[116:119]
	s_waitcnt lgkmcnt(0)
	v_mfma_f32_16x16x32_bf16 v[120:123], v[176:179], v[160:163], v[120:123]
	v_mfma_f32_16x16x32_bf16 v[100:103], v[168:171], v[156:159], v[100:103]
	v_mfma_f32_16x16x32_bf16 v[104:107], v[176:179], v[156:159], v[104:107]
	v_mfma_f32_16x16x32_bf16 v[84:87], v[168:171], v[152:155], v[84:87]
	v_mfma_f32_16x16x32_bf16 v[88:91], v[176:179], v[152:155], v[88:91]
	v_mfma_f32_16x16x32_bf16 v[72:75], v[168:171], v[148:151], v[72:75]
	v_mfma_f32_16x16x32_bf16 v[68:71], v[176:179], v[148:151], v[68:71]
	v_cndmask_b32_e64 v198, 0, 1, s[34:35]
	v_cmp_ne_u32_e64 s[14:15], 1, v198
	s_andn2_b64 vcc, exec, s[34:35]
	s_barrier
	s_cbranch_vccnz .LBB0_1319
	ds_read_b128 v[144:147], v221 offset:16384
	ds_read_b128 v[160:163], v221 offset:17408
	ds_read_b128 v[140:143], v221 offset:18432
	ds_read_b128 v[156:159], v221 offset:19456
	ds_read_b128 v[136:139], v221 offset:20480
	ds_read_b128 v[152:155], v221 offset:21504
	ds_read_b128 v[132:135], v221 offset:22528
	ds_read_b128 v[148:151], v221 offset:23552

; #define G8_STAGE(bufoff, gbase, voff) do { _Pragma("unroll") for (int _i = 0; _i < 2; ++_i) \
;         __builtin_amdgcn_global_load_lds((const unsigned*)((const char*)(gbase) + (voff)[_i]), (LAS unsigned*)(lds + (bufoff) + ldsw + _i * 8192), 16, 0, 0); } while (0)
; #define G8_LDA(dst, b, h) do { _Pragma("unroll") for (int m = 0; m < 4; ++m) _Pragma("unroll") for (int k = 0; k < 2; ++k) dst[m][k] = *(const LAS bf16x8*)(lds + G8_SA(b, h) + aoff + m * 2048 + k * 1024); } while (0)
; #define G8_LDB(dst, b, h) do { _Pragma("unroll") for (int n = 0; n < 2; ++n) _Pragma("unroll") for (int k = 0; k < 2; ++k) dst[n][k] = *(const LAS bf16x8*)(lds + G8_SB(b, h) + boff + n * 2048 + k * 1024); } while (0)
; #define G8_MMA(ai, bj, At, Bt) do { __builtin_amdgcn_s_setprio(1); _Pragma("unroll") for (int m = 0; m < 4; ++m) _Pragma("unroll") for (int n = 0; n < 2; ++n) _Pragma("unroll") for (int k = 0; k < 2; ++k) \
;         acc[ai][bj][m][n] = __builtin_amdgcn_mfma_f32_16x16x32_bf16(Bt[n][k], At[m][k], acc[ai][bj][m][n], 0, 0, 0); __builtin_amdgcn_s_setprio(0); } while (0)
; #define G8_WAIT_L(n) asm volatile("s_waitcnt lgkmcnt(" #n ")" ::: "memory")
; #define G8_BAR __builtin_amdgcn_s_barrier()
; #define G8_SCHED __builtin_amdgcn_sched_barrier(0)
; template <class Epi, class Sched>
; __device__ __forceinline__ void gemm_phase(int wv, LAS unsigned char* lds, const int K, const Sched& S, const Epi& E) {
;     ...
;             G8_LDB(B0, 1, 0); G8_SCHED; G8_LDA(At, 1, 0); G8_STAGE(G8_SA(0, 1), a2 + hstep, voffA);
;             G8_WAIT_L(8); G8_BAR; G8_WAIT_L(0); G8_MMA(0, 0, At, B0); G8_BAR; G8_SCHED;
;             G8_LDB(B1, 1, 1); G8_STAGE(G8_SB(1, 0), b3, voffB);
;             G8_BAR; G8_WAIT_L(0); G8_MMA(0, 1, At, B1); G8_BAR;
.LBB0_1323:
	s_add_i32 s76, 0, 0x18000
	s_waitcnt lgkmcnt(0)
	v_add_u32_e32 v132, s76, v220
	s_barrier
	ds_read_b128 v[180:183], v132
	ds_read_b128 v[184:187], v132 offset:1024
	ds_read_b128 v[188:191], v132 offset:2048
	ds_read_b128 v[192:195], v132 offset:3072
	s_add_u32 s40, s40, 0x40000
	s_addc_u32 s41, s41, 0
	s_mov_b32 m0, s48
	v_lshl_add_u64 v[164:165], s[40:41], 0, v[206:207]
	ds_read_b128 v[144:147], v221 offset:32768
	ds_read_b128 v[160:163], v221 offset:33792
	ds_read_b128 v[140:143], v221 offset:34816
	ds_read_b128 v[156:159], v221 offset:35840
	ds_read_b128 v[136:139], v221 offset:36864
	ds_read_b128 v[152:155], v221 offset:37888
	ds_read_b128 v[132:135], v221 offset:38912
	ds_read_b128 v[148:151], v221 offset:39936
	global_load_lds_dwordx4 v[164:165], off
	v_lshl_add_u64 v[164:165], s[40:41], 0, v[208:209]
	s_mov_b32 m0, s49
	s_nop 0
	global_load_lds_dwordx4 v[164:165], off
	s_waitcnt lgkmcnt(8)
	s_barrier
	s_waitcnt lgkmcnt(7)
	v_mfma_f32_16x16x32_bf16 v[124:127], v[180:183], v[144:147], v[124:127]
	v_mfma_f32_16x16x32_bf16 v[128:131], v[188:191], v[144:147], v[128:131]
	s_waitcnt lgkmcnt(5)
	v_mfma_f32_16x16x32_bf16 v[108:111], v[180:183], v[140:143], v[108:111]
	v_mfma_f32_16x16x32_bf16 v[112:115], v[188:191], v[140:143], v[112:115]
	s_waitcnt lgkmcnt(3)
	v_mfma_f32_16x16x32_bf16 v[92:95], v[180:183], v[136:139], v[92:95]
	v_mfma_f32_16x16x32_bf16 v[96:99], v[188:191], v[136:139], v[96:99]
	s_waitcnt lgkmcnt(1)
	v_mfma_f32_16x16x32_bf16 v[76:79], v[180:183], v[132:135], v[76:79]
	v_mfma_f32_16x16x32_bf16 v[80:83], v[188:191], v[132:135], v[80:83]
	v_mfma_f32_16x16x32_bf16 v[124:127], v[184:187], v[160:163], v[124:127]
	v_mfma_f32_16x16x32_bf16 v[128:131], v[192:195], v[160:163], v[128:131]
	v_mfma_f32_16x16x32_bf16 v[108:111], v[184:187], v[156:159], v[108:111]
	v_mfma_f32_16x16x32_bf16 v[112:115], v[192:195], v[156:159], v[112:115]
	v_mfma_f32_16x16x32_bf16 v[92:95], v[184:187], v[152:155], v[92:95]
	v_mfma_f32_16x16x32_bf16 v[96:99], v[192:195], v[152:155], v[96:99]
	s_waitcnt lgkmcnt(0)
	v_mfma_f32_16x16x32_bf16 v[76:79], v[184:187], v[148:151], v[76:79]
	v_mfma_f32_16x16x32_bf16 v[80:83], v[192:195], v[148:151], v[80:83]
	s_barrier
	s_add_i32 s40, s76, s3
	v_add_u32_e32 v0, 0x1c000, v0
	v_lshl_add_u64 v[2:3], v[2:3], 0, s[58:59]
	s_mov_b32 m0, s40
	ds_read_b128 v[164:167], v0
	ds_read_b128 v[168:171], v0 offset:1024
	ds_read_b128 v[172:175], v0 offset:2048
	ds_read_b128 v[176:179], v0 offset:3072
	global_load_lds_dwordx4 v[2:3], off
	v_lshl_add_u64 v[2:3], v[214:215], 0, s[58:59]
	s_add_i32 m0, s40, 0x2000
	s_nop 0
	global_load_lds_dwordx4 v[2:3], off
	s_barrier
	s_waitcnt lgkmcnt(3)
	v_mfma_f32_16x16x32_bf16 v[116:119], v[164:167], v[144:147], v[116:119]
	s_waitcnt lgkmcnt(1)
	v_mfma_f32_16x16x32_bf16 v[120:123], v[172:175], v[144:147], v[120:123]
	v_mfma_f32_16x16x32_bf16 v[100:103], v[164:167], v[140:143], v[100:103]
	v_mfma_f32_16x16x32_bf16 v[104:107], v[172:175], v[140:143], v[104:107]
	v_mfma_f32_16x16x32_bf16 v[84:87], v[164:167], v[136:139], v[84:87]
	v_mfma_f32_16x16x32_bf16 v[88:91], v[172:175], v[136:139], v[88:91]
	v_mfma_f32_16x16x32_bf16 v[72:75], v[164:167], v[132:135], v[72:75]
	v_mfma_f32_16x16x32_bf16 v[68:71], v[172:175], v[132:135], v[68:71]
	v_mfma_f32_16x16x32_bf16 v[116:119], v[168:171], v[160:163], v[116:119]
	s_waitcnt lgkmcnt(0)
	v_mfma_f32_16x16x32_bf16 v[120:123], v[176:179], v[160:163], v[120:123]
	v_mfma_f32_16x16x32_bf16 v[100:103], v[168:171], v[156:159], v[100:103]
	v_mfma_f32_16x16x32_bf16 v[104:107], v[176:179], v[156:159], v[104:107]
	v_mfma_f32_16x16x32_bf16 v[84:87], v[168:171], v[152:155], v[84:87]
	v_mfma_f32_16x16x32_bf16 v[88:91], v[176:179], v[152:155], v[88:91]
	v_mfma_f32_16x16x32_bf16 v[72:75], v[168:171], v[148:151], v[72:75]
	v_mfma_f32_16x16x32_bf16 v[68:71], v[176:179], v[148:151], v[68:71]
	s_cmp_eq_u32 s101, 1
	s_cbranch_scc0 .Lp8rx_c
	s_waitcnt vmcnt(10)

; #define G8_STAGE(bufoff, gbase, voff) do { _Pragma("unroll") for (int _i = 0; _i < 2; ++_i) \
;         __builtin_amdgcn_global_load_lds((const unsigned*)((const char*)(gbase) + (voff)[_i]), (LAS unsigned*)(lds + (bufoff) + ldsw + _i * 8192), 16, 0, 0); } while (0)
; #define G8_LDA(dst, b, h) do { _Pragma("unroll") for (int m = 0; m < 4; ++m) _Pragma("unroll") for (int k = 0; k < 2; ++k) dst[m][k] = *(const LAS bf16x8*)(lds + G8_SA(b, h) + aoff + m * 2048 + k * 1024); } while (0)
; #define G8_LDB(dst, b, h) do { _Pragma("unroll") for (int n = 0; n < 2; ++n) _Pragma("unroll") for (int k = 0; k < 2; ++k) dst[n][k] = *(const LAS bf16x8*)(lds + G8_SB(b, h) + boff + n * 2048 + k * 1024); } while (0)
; #define G8_MMA(ai, bj, At, Bt) do { __builtin_amdgcn_s_setprio(1); _Pragma("unroll") for (int m = 0; m < 4; ++m) _Pragma("unroll") for (int n = 0; n < 2; ++n) _Pragma("unroll") for (int k = 0; k < 2; ++k) \
;         acc[ai][bj][m][n] = __builtin_amdgcn_mfma_f32_16x16x32_bf16(Bt[n][k], At[m][k], acc[ai][bj][m][n], 0, 0, 0); __builtin_amdgcn_s_setprio(0); } while (0)
; #define G8_WAIT_V(n) asm volatile("s_waitcnt vmcnt(" #n ")" ::: "memory")
; #define G8_WAIT_L(n) asm volatile("s_waitcnt lgkmcnt(" #n ")" ::: "memory")
; template <class Epi, class Sched>
; __device__ __forceinline__ void gemm_phase(int wv, LAS unsigned char* lds, const int K, const Sched& S, const Epi& E) {
;     ...
;         for (int t = 0; t < nt; t += 2) {
;             const bool last = (t == nt - 2);
;             const char* a1 = cA + (size_t)(t + 1) * kstep;
;             const char* a2 = last ? nA : cA + (size_t)(t + 2) * kstep; const char* b2 = last ? nB : cB + (size_t)(t + 2) * kstep;
;             const char* a3 = a2 + kstep; const char* b3 = b2 + kstep;
;             G8_LDB(B0, 0, 0); G8_SCHED; G8_LDA(At, 0, 0); G8_STAGE(G8_SA(1, 1), a1 + hstep, voffA);
;             G8_WAIT_L(8); G8_BAR; G8_WAIT_L(0); G8_MMA(0, 0, At, B0); G8_BAR; G8_SCHED;
;             G8_LDB(B1, 0, 1); G8_STAGE(G8_SB(0, 0), b2, voffB);
;             G8_BAR; G8_WAIT_L(0); G8_MMA(0, 1, At, B1); G8_BAR;
;             if (full) G8_LDA(At, 0, 1); G8_STAGE(G8_SA(0, 0), a2, voffA);
;             G8_BAR; G8_WAIT_L(0); if (full) G8_MMA(1, 0, At, B0); G8_BAR; G8_SCHED;
;             G8_STAGE(G8_SB(0, 1), b2 + hstep, voffB);
;             G8_WAIT_V(6); G8_BAR; if (full) G8_MMA(1, 1, At, B1); G8_BAR;
.LBB0_1432:
	s_add_i32 s41, s30, 2
	s_add_u32 s28, s26, 0x100
	s_addc_u32 s29, s27, 0
	s_add_i32 s42, 0, 0x10000
	v_add_u32_e32 v0, s42, v182
	ds_read_b128 v[106:109], v0
	ds_read_b128 v[110:113], v0 offset:1024
	ds_read_b128 v[122:125], v0 offset:2048
	ds_read_b128 v[126:129], v0 offset:3072
	s_cmp_eq_u32 s38, s30
	s_cselect_b32 s30, s37, s39
	s_cselect_b32 s35, s4, s29
	s_cselect_b32 s34, s5, s28
	s_cselect_b32 s31, s36, s40
	v_lshl_add_u64 v[192:193], s[26:27], 0, v[166:167]
	s_add_i32 m0, s60, 0xc000
	ds_read_b128 v[146:149], v183
	ds_read_b128 v[150:153], v183 offset:1024
	ds_read_b128 v[154:157], v183 offset:2048
	ds_read_b128 v[170:173], v183 offset:3072
	ds_read_b128 v[174:177], v183 offset:4096
	ds_read_b128 v[178:181], v183 offset:5120
	ds_read_b128 v[184:187], v183 offset:6144
	ds_read_b128 v[188:191], v183 offset:7168
	global_load_lds_dwordx4 v[192:193], off
	v_lshl_add_u64 v[192:193], s[26:27], 0, v[168:169]
	s_add_i32 m0, s60, 0xe000
	s_nop 0
	global_load_lds_dwordx4 v[192:193], off
	s_waitcnt lgkmcnt(8)
	s_barrier
	s_waitcnt lgkmcnt(0)
	s_waitcnt lgkmcnt(0)
	v_mfma_f32_16x16x32_bf16 v[142:145], v[106:109], v[146:149], v[142:145]
	v_mfma_f32_16x16x32_bf16 v[138:141], v[122:125], v[146:149], v[138:141]
	v_mfma_f32_16x16x32_bf16 v[118:121], v[106:109], v[154:157], v[118:121]
	v_mfma_f32_16x16x32_bf16 v[114:117], v[122:125], v[154:157], v[114:117]
	v_mfma_f32_16x16x32_bf16 v[94:97], v[106:109], v[174:177], v[94:97]
	v_mfma_f32_16x16x32_bf16 v[90:93], v[122:125], v[174:177], v[90:93]
	v_mfma_f32_16x16x32_bf16 v[78:81], v[106:109], v[184:187], v[78:81]
	v_mfma_f32_16x16x32_bf16 v[74:77], v[122:125], v[184:187], v[74:77]
	v_mfma_f32_16x16x32_bf16 v[142:145], v[110:113], v[150:153], v[142:145]
	v_mfma_f32_16x16x32_bf16 v[138:141], v[126:129], v[150:153], v[138:141]
	v_mfma_f32_16x16x32_bf16 v[118:121], v[110:113], v[170:173], v[118:121]
	v_mfma_f32_16x16x32_bf16 v[114:117], v[126:129], v[170:173], v[114:117]
	v_mfma_f32_16x16x32_bf16 v[94:97], v[110:113], v[178:181], v[94:97]
	v_mfma_f32_16x16x32_bf16 v[90:93], v[126:129], v[178:181], v[90:93]
	v_mfma_f32_16x16x32_bf16 v[78:81], v[110:113], v[188:191], v[78:81]
	v_mfma_f32_16x16x32_bf16 v[74:77], v[126:129], v[188:191], v[74:77]
	s_barrier
	s_add_i32 s43, 0, 0x14000
	s_add_i32 s26, s42, s3
	v_add_u32_e32 v0, s43, v182
	v_lshl_add_u64 v[204:205], s[30:31], 0, v[160:161]
	s_mov_b32 m0, s26
	ds_read_b128 v[192:195], v0
	ds_read_b128 v[198:201], v0 offset:1024
	ds_read_b128 v[206:209], v0 offset:2048
	ds_read_b128 v[210:213], v0 offset:3072
	global_load_lds_dwordx4 v[204:205], off
	v_lshl_add_u64 v[214:215], s[30:31], 0, v[164:165]
	s_add_i32 m0, s26, 0x2000
	s_nop 0
	global_load_lds_dwordx4 v[214:215], off
	s_barrier
	s_waitcnt lgkmcnt(3)
	v_mfma_f32_16x16x32_bf16 v[134:137], v[192:195], v[146:149], v[134:137]
	s_waitcnt lgkmcnt(1)
	v_mfma_f32_16x16x32_bf16 v[130:133], v[206:209], v[146:149], v[130:133]
	v_mfma_f32_16x16x32_bf16 v[102:105], v[192:195], v[154:157], v[102:105]
	v_mfma_f32_16x16x32_bf16 v[98:101], v[206:209], v[154:157], v[98:101]
	v_mfma_f32_16x16x32_bf16 v[86:89], v[192:195], v[174:177], v[86:89]
	v_mfma_f32_16x16x32_bf16 v[82:85], v[206:209], v[174:177], v[82:85]
	v_mfma_f32_16x16x32_bf16 v[70:73], v[192:195], v[184:187], v[70:73]
	v_mfma_f32_16x16x32_bf16 v[66:69], v[206:209], v[184:187], v[66:69]
	v_mfma_f32_16x16x32_bf16 v[134:137], v[198:201], v[150:153], v[134:137]
	s_waitcnt lgkmcnt(0)
	v_mfma_f32_16x16x32_bf16 v[130:133], v[210:213], v[150:153], v[130:133]
	v_mfma_f32_16x16x32_bf16 v[102:105], v[198:201], v[170:173], v[102:105]
	v_mfma_f32_16x16x32_bf16 v[98:101], v[210:213], v[170:173], v[98:101]
	v_mfma_f32_16x16x32_bf16 v[86:89], v[198:201], v[178:181], v[86:89]
	v_mfma_f32_16x16x32_bf16 v[82:85], v[210:213], v[178:181], v[82:85]
	v_mfma_f32_16x16x32_bf16 v[70:73], v[198:201], v[188:191], v[70:73]
	v_mfma_f32_16x16x32_bf16 v[66:69], v[210:213], v[188:191], v[66:69]
	s_mov_b32 m0, s60
	v_lshl_add_u64 v[216:217], s[34:35], 0, v[158:159]
	s_barrier
	ds_read_b128 v[146:149], v183 offset:16384
	ds_read_b128 v[150:153], v183 offset:17408
	ds_read_b128 v[154:157], v183 offset:18432
	ds_read_b128 v[170:173], v183 offset:19456
	ds_read_b128 v[174:177], v183 offset:20480
	ds_read_b128 v[178:181], v183 offset:21504
	ds_read_b128 v[184:187], v183 offset:22528
	ds_read_b128 v[188:191], v183 offset:23552
	global_load_lds_dwordx4 v[216:217], off
	v_lshl_add_u64 v[218:219], s[34:35], 0, v[162:163]
	s_mov_b32 m0, s61
	s_nop 0
	global_load_lds_dwordx4 v[218:219], off
	s_barrier
	s_waitcnt lgkmcnt(7)
	v_mfma_f32_16x16x32_bf16 v[62:65], v[106:109], v[146:149], v[62:65]
	v_mfma_f32_16x16x32_bf16 v[58:61], v[122:125], v[146:149], v[58:61]
	s_waitcnt lgkmcnt(5)
	v_mfma_f32_16x16x32_bf16 v[46:49], v[106:109], v[154:157], v[46:49]
	v_mfma_f32_16x16x32_bf16 v[42:45], v[122:125], v[154:157], v[42:45]
	s_waitcnt lgkmcnt(3)
	v_mfma_f32_16x16x32_bf16 v[30:33], v[106:109], v[174:177], v[30:33]
	v_mfma_f32_16x16x32_bf16 v[26:29], v[122:125], v[174:177], v[26:29]
	s_waitcnt lgkmcnt(1)
	v_mfma_f32_16x16x32_bf16 v[14:17], v[106:109], v[184:187], v[14:17]
	v_mfma_f32_16x16x32_bf16 v[10:13], v[122:125], v[184:187], v[10:13]
	v_mfma_f32_16x16x32_bf16 v[62:65], v[110:113], v[150:153], v[62:65]
	v_mfma_f32_16x16x32_bf16 v[58:61], v[126:129], v[150:153], v[58:61]
	v_mfma_f32_16x16x32_bf16 v[46:49], v[110:113], v[170:173], v[46:49]
	v_mfma_f32_16x16x32_bf16 v[42:45], v[126:129], v[170:173], v[42:45]
	v_mfma_f32_16x16x32_bf16 v[30:33], v[110:113], v[178:181], v[30:33]
	v_mfma_f32_16x16x32_bf16 v[26:29], v[126:129], v[178:181], v[26:29]
	s_waitcnt lgkmcnt(0)
	v_mfma_f32_16x16x32_bf16 v[14:17], v[110:113], v[188:191], v[14:17]
	v_mfma_f32_16x16x32_bf16 v[10:13], v[126:129], v[188:191], v[10:13]
	s_barrier
; #define G8_STAGE(bufoff, gbase, voff) do { _Pragma("unroll") for (int _i = 0; _i < 2; ++_i) \
;         __builtin_amdgcn_global_load_lds((const unsigned*)((const char*)(gbase) + (voff)[_i]), (LAS unsigned*)(lds + (bufoff) + ldsw + _i * 8192), 16, 0, 0); } while (0)
; #define G8_LDA(dst, b, h) do { _Pragma("unroll") for (int m = 0; m < 4; ++m) _Pragma("unroll") for (int k = 0; k < 2; ++k) dst[m][k] = *(const LAS bf16x8*)(lds + G8_SA(b, h) + aoff + m * 2048 + k * 1024); } while (0)
; #define G8_LDB(dst, b, h) do { _Pragma("unroll") for (int n = 0; n < 2; ++n) _Pragma("unroll") for (int k = 0; k < 2; ++k) dst[n][k] = *(const LAS bf16x8*)(lds + G8_SB(b, h) + boff + n * 2048 + k * 1024); } while (0)
; #define G8_MMA(ai, bj, At, Bt) do { __builtin_amdgcn_s_setprio(1); _Pragma("unroll") for (int m = 0; m < 4; ++m) _Pragma("unroll") for (int n = 0; n < 2; ++n) _Pragma("unroll") for (int k = 0; k < 2; ++k) \
;         acc[ai][bj][m][n] = __builtin_amdgcn_mfma_f32_16x16x32_bf16(Bt[n][k], At[m][k], acc[ai][bj][m][n], 0, 0, 0); __builtin_amdgcn_s_setprio(0); } while (0)
; #define G8_WAIT_V(n) asm volatile("s_waitcnt vmcnt(" #n ")" ::: "memory")
; #define G8_WAIT_L(n) asm volatile("s_waitcnt lgkmcnt(" #n ")" ::: "memory")
; #define G8_BAR __builtin_amdgcn_s_barrier()
; #define G8_SCHED __builtin_amdgcn_sched_barrier(0)
; template <class Epi, class Sched>
; __device__ __forceinline__ void gemm_phase(int wv, LAS unsigned char* lds, const int K, const Sched& S, const Epi& E) {
;     ...
;             G8_STAGE(G8_SB(0, 1), b2 + hstep, voffB);
;             G8_WAIT_V(6); G8_BAR; if (full) G8_MMA(1, 1, At, B1); G8_BAR;
;             G8_LDB(B0, 1, 0); G8_SCHED; G8_LDA(At, 1, 0); G8_STAGE(G8_SA(0, 1), a2 + hstep, voffA);
;             G8_WAIT_L(8); G8_BAR; G8_WAIT_L(0); G8_MMA(0, 0, At, B0); G8_BAR; G8_SCHED;
;             G8_LDB(B1, 1, 1); G8_STAGE(G8_SB(1, 0), b3, voffB);
;             G8_BAR; G8_WAIT_L(0); G8_MMA(0, 1, At, B1); G8_BAR;
;             if (full) G8_LDA(At, 1, 1); G8_STAGE(G8_SA(1, 0), a3, voffA);
;             G8_BAR; G8_WAIT_L(0); if (full) G8_MMA(1, 0, At, B0); G8_BAR; G8_SCHED;
	s_add_u32 s26, s30, 0xb0000
	s_addc_u32 s27, s31, 0
	s_add_i32 s42, s43, s3
	v_lshl_add_u64 v[106:107], s[26:27], 0, v[160:161]
	s_mov_b32 m0, s42
	s_nop 0
	global_load_lds_dwordx4 v[106:107], off
	v_lshl_add_u64 v[106:107], s[26:27], 0, v[164:165]
	s_add_i32 m0, s42, 0x2000
	s_nop 0
	global_load_lds_dwordx4 v[106:107], off
	s_waitcnt vmcnt(6)
	s_barrier
	v_mfma_f32_16x16x32_bf16 v[54:57], v[192:195], v[146:149], v[54:57]
	v_mfma_f32_16x16x32_bf16 v[50:53], v[206:209], v[146:149], v[50:53]
	v_mfma_f32_16x16x32_bf16 v[38:41], v[192:195], v[154:157], v[38:41]
	v_mfma_f32_16x16x32_bf16 v[34:37], v[206:209], v[154:157], v[34:37]
	v_mfma_f32_16x16x32_bf16 v[22:25], v[192:195], v[174:177], v[22:25]
	v_mfma_f32_16x16x32_bf16 v[18:21], v[206:209], v[174:177], v[18:21]
	v_mfma_f32_16x16x32_bf16 v[6:9], v[192:195], v[184:187], v[6:9]
	v_mfma_f32_16x16x32_bf16 v[2:5], v[206:209], v[184:187], v[2:5]
	v_mfma_f32_16x16x32_bf16 v[54:57], v[198:201], v[150:153], v[54:57]
	v_mfma_f32_16x16x32_bf16 v[50:53], v[210:213], v[150:153], v[50:53]
	v_mfma_f32_16x16x32_bf16 v[38:41], v[198:201], v[170:173], v[38:41]
	v_mfma_f32_16x16x32_bf16 v[34:37], v[210:213], v[170:173], v[34:37]
	v_mfma_f32_16x16x32_bf16 v[22:25], v[198:201], v[178:181], v[22:25]
	v_mfma_f32_16x16x32_bf16 v[18:21], v[210:213], v[178:181], v[18:21]
	v_mfma_f32_16x16x32_bf16 v[6:9], v[198:201], v[188:191], v[6:9]
	v_mfma_f32_16x16x32_bf16 v[2:5], v[210:213], v[188:191], v[2:5]
	s_add_i32 s42, 0, 0x18000
	v_add_u32_e32 v0, s42, v182
	s_barrier
	ds_read_b128 v[106:109], v0
	ds_read_b128 v[110:113], v0 offset:1024
	ds_read_b128 v[122:125], v0 offset:2048
	ds_read_b128 v[126:129], v0 offset:3072
	s_add_u32 s26, s34, 0xb0000
	s_addc_u32 s27, s35, 0
	s_mov_b32 m0, s63
	v_lshl_add_u64 v[192:193], s[26:27], 0, v[158:159]
	ds_read_b128 v[146:149], v183 offset:32768
	ds_read_b128 v[150:153], v183 offset:33792
	ds_read_b128 v[154:157], v183 offset:34816
	ds_read_b128 v[170:173], v183 offset:35840
	ds_read_b128 v[174:177], v183 offset:36864
	ds_read_b128 v[178:181], v183 offset:37888
	ds_read_b128 v[184:187], v183 offset:38912
	ds_read_b128 v[188:191], v183 offset:39936
	global_load_lds_dwordx4 v[192:193], off
	v_lshl_add_u64 v[192:193], s[26:27], 0, v[162:163]
	s_mov_b32 m0, s64
	s_nop 0
	global_load_lds_dwordx4 v[192:193], off
	s_waitcnt lgkmcnt(8)
	s_barrier
	s_waitcnt lgkmcnt(7)
	v_mfma_f32_16x16x32_bf16 v[142:145], v[106:109], v[146:149], v[142:145]
	v_mfma_f32_16x16x32_bf16 v[138:141], v[122:125], v[146:149], v[138:141]
	s_waitcnt lgkmcnt(5)
	v_mfma_f32_16x16x32_bf16 v[118:121], v[106:109], v[154:157], v[118:121]
	v_mfma_f32_16x16x32_bf16 v[114:117], v[122:125], v[154:157], v[114:117]
	s_waitcnt lgkmcnt(3)
	v_mfma_f32_16x16x32_bf16 v[94:97], v[106:109], v[174:177], v[94:97]
	v_mfma_f32_16x16x32_bf16 v[90:93], v[122:125], v[174:177], v[90:93]
	s_waitcnt lgkmcnt(1)
	v_mfma_f32_16x16x32_bf16 v[78:81], v[106:109], v[184:187], v[78:81]
	v_mfma_f32_16x16x32_bf16 v[74:77], v[122:125], v[184:187], v[74:77]
	v_mfma_f32_16x16x32_bf16 v[142:145], v[110:113], v[150:153], v[142:145]
	v_mfma_f32_16x16x32_bf16 v[138:141], v[126:129], v[150:153], v[138:141]
	v_mfma_f32_16x16x32_bf16 v[118:121], v[110:113], v[170:173], v[118:121]
	v_mfma_f32_16x16x32_bf16 v[114:117], v[126:129], v[170:173], v[114:117]
	v_mfma_f32_16x16x32_bf16 v[94:97], v[110:113], v[178:181], v[94:97]
	v_mfma_f32_16x16x32_bf16 v[90:93], v[126:129], v[178:181], v[90:93]
	s_waitcnt lgkmcnt(0)
	v_mfma_f32_16x16x32_bf16 v[78:81], v[110:113], v[188:191], v[78:81]
	v_mfma_f32_16x16x32_bf16 v[74:77], v[126:129], v[188:191], v[74:77]
	s_barrier
	s_add_i32 s34, 0, 0x1c000
	s_add_i32 s26, s42, s3
	v_add_u32_e32 v0, s34, v182
	v_lshl_add_u64 v[204:205], v[204:205], 0, s[58:59]
	s_mov_b32 m0, s26
	ds_read_b128 v[192:195], v0
	ds_read_b128 v[198:201], v0 offset:1024
	ds_read_b128 v[206:209], v0 offset:2048
	ds_read_b128 v[210:213], v0 offset:3072
	global_load_lds_dwordx4 v[204:205], off
	v_lshl_add_u64 v[204:205], v[214:215], 0, s[58:59]
	s_add_i32 m0, s26, 0x2000
	s_nop 0
	global_load_lds_dwordx4 v[204:205], off
	s_barrier
	s_waitcnt lgkmcnt(3)
	v_mfma_f32_16x16x32_bf16 v[134:137], v[192:195], v[146:149], v[134:137]
	s_waitcnt lgkmcnt(1)
	v_mfma_f32_16x16x32_bf16 v[130:133], v[206:209], v[146:149], v[130:133]
	v_mfma_f32_16x16x32_bf16 v[102:105], v[192:195], v[154:157], v[102:105]
	v_mfma_f32_16x16x32_bf16 v[98:101], v[206:209], v[154:157], v[98:101]
	v_mfma_f32_16x16x32_bf16 v[86:89], v[192:195], v[174:177], v[86:89]
	v_mfma_f32_16x16x32_bf16 v[82:85], v[206:209], v[174:177], v[82:85]
	v_mfma_f32_16x16x32_bf16 v[70:73], v[192:195], v[184:187], v[70:73]
	v_mfma_f32_16x16x32_bf16 v[66:69], v[206:209], v[184:187], v[66:69]
	v_mfma_f32_16x16x32_bf16 v[134:137], v[198:201], v[150:153], v[134:137]
	s_waitcnt lgkmcnt(0)
	v_mfma_f32_16x16x32_bf16 v[130:133], v[210:213], v[150:153], v[130:133]
	v_mfma_f32_16x16x32_bf16 v[102:105], v[198:201], v[170:173], v[102:105]
	v_mfma_f32_16x16x32_bf16 v[98:101], v[210:213], v[170:173], v[98:101]
	v_mfma_f32_16x16x32_bf16 v[86:89], v[198:201], v[178:181], v[86:89]
	v_mfma_f32_16x16x32_bf16 v[82:85], v[210:213], v[178:181], v[82:85]
	v_mfma_f32_16x16x32_bf16 v[70:73], v[198:201], v[188:191], v[70:73]
	v_mfma_f32_16x16x32_bf16 v[66:69], v[210:213], v[188:191], v[66:69]
	s_mov_b32 m0, s67
	v_lshl_add_u64 v[204:205], v[216:217], 0, s[58:59]
	s_barrier
	ds_read_b128 v[146:149], v183 offset:49152
	ds_read_b128 v[150:153], v183 offset:50176
	ds_read_b128 v[154:157], v183 offset:51200
	ds_read_b128 v[170:173], v183 offset:52224
	ds_read_b128 v[174:177], v183 offset:53248
	ds_read_b128 v[178:181], v183 offset:54272
	ds_read_b128 v[184:187], v183 offset:55296
	ds_read_b128 v[188:191], v183 offset:56320
	global_load_lds_dwordx4 v[204:205], off
	v_lshl_add_u64 v[204:205], v[218:219], 0, s[58:59]
	s_mov_b32 m0, s72
	s_nop 0
	global_load_lds_dwordx4 v[204:205], off
	s_barrier
; __device__ __forceinline__ int otid(int wv) { int ln; asm volatile("v_mbcnt_lo_u32_b32 %0, -1, 0\n\tv_mbcnt_hi_u32_b32 %0, -1, %0" : "=v"(ln)); return wv * 64 + ln; }
; #define G8_STAGE(bufoff, gbase, voff) do { _Pragma("unroll") for (int _i = 0; _i < 2; ++_i) \
;         __builtin_amdgcn_global_load_lds((const unsigned*)((const char*)(gbase) + (voff)[_i]), (LAS unsigned*)(lds + (bufoff) + ldsw + _i * 8192), 16, 0, 0); } while (0)
; #define G8_MMA(ai, bj, At, Bt) do { __builtin_amdgcn_s_setprio(1); _Pragma("unroll") for (int m = 0; m < 4; ++m) _Pragma("unroll") for (int n = 0; n < 2; ++n) _Pragma("unroll") for (int k = 0; k < 2; ++k) \
;         acc[ai][bj][m][n] = __builtin_amdgcn_mfma_f32_16x16x32_bf16(Bt[n][k], At[m][k], acc[ai][bj][m][n], 0, 0, 0); __builtin_amdgcn_s_setprio(0); } while (0)
; #define G8_WAIT_V(n) asm volatile("s_waitcnt vmcnt(" #n ")" ::: "memory")
; #define G8_WAIT_L(n) asm volatile("s_waitcnt lgkmcnt(" #n ")" ::: "memory")
; #define G8_BAR __builtin_amdgcn_s_barrier()
; #define G8_SCHED __builtin_amdgcn_sched_barrier(0)
; template <class Epi, class Sched>
; __device__ __forceinline__ void gemm_phase(int wv, LAS unsigned char* lds, const int K, const Sched& S, const Epi& E) {
;     ...
;             G8_BAR; G8_WAIT_L(0); if (full) G8_MMA(1, 0, At, B0); G8_BAR; G8_SCHED;
;             G8_STAGE(G8_SB(1, 1), b3 + hstep, voffB);
;             G8_WAIT_V(6); G8_BAR; if (full) G8_MMA(1, 1, At, B1); G8_BAR;
;         }
;         { const int t2 = otid(wv); E(acc, cur, wr, wc, t2 & 15, (t2 >> 4) & 3); }
;         if (!has_next) break;
	s_waitcnt lgkmcnt(7)
	v_mfma_f32_16x16x32_bf16 v[62:65], v[106:109], v[146:149], v[62:65]
	v_mfma_f32_16x16x32_bf16 v[58:61], v[122:125], v[146:149], v[58:61]
	s_waitcnt lgkmcnt(5)
	v_mfma_f32_16x16x32_bf16 v[46:49], v[106:109], v[154:157], v[46:49]
	v_mfma_f32_16x16x32_bf16 v[42:45], v[122:125], v[154:157], v[42:45]
	s_waitcnt lgkmcnt(3)
	v_mfma_f32_16x16x32_bf16 v[30:33], v[106:109], v[174:177], v[30:33]
	v_mfma_f32_16x16x32_bf16 v[26:29], v[122:125], v[174:177], v[26:29]
	s_waitcnt lgkmcnt(1)
	v_mfma_f32_16x16x32_bf16 v[14:17], v[106:109], v[184:187], v[14:17]
	v_mfma_f32_16x16x32_bf16 v[10:13], v[122:125], v[184:187], v[10:13]
	v_mfma_f32_16x16x32_bf16 v[62:65], v[110:113], v[150:153], v[62:65]
	v_mfma_f32_16x16x32_bf16 v[58:61], v[126:129], v[150:153], v[58:61]
	v_mfma_f32_16x16x32_bf16 v[46:49], v[110:113], v[170:173], v[46:49]
	v_mfma_f32_16x16x32_bf16 v[42:45], v[126:129], v[170:173], v[42:45]
	v_mfma_f32_16x16x32_bf16 v[30:33], v[110:113], v[178:181], v[30:33]
	v_mfma_f32_16x16x32_bf16 v[26:29], v[126:129], v[178:181], v[26:29]
	s_waitcnt lgkmcnt(0)
	v_mfma_f32_16x16x32_bf16 v[14:17], v[110:113], v[188:191], v[14:17]
	v_mfma_f32_16x16x32_bf16 v[10:13], v[126:129], v[188:191], v[10:13]
	s_barrier
	s_add_u32 s26, s30, 0xb0080
	s_addc_u32 s27, s31, 0
	s_add_i32 s30, s34, s3
	v_lshl_add_u64 v[106:107], s[26:27], 0, v[160:161]
	s_mov_b32 m0, s30
	s_nop 0
	global_load_lds_dwordx4 v[106:107], off
	v_lshl_add_u64 v[106:107], s[26:27], 0, v[164:165]
	s_add_i32 m0, s30, 0x2000
	s_nop 0
	global_load_lds_dwordx4 v[106:107], off
	s_waitcnt vmcnt(6)
	s_barrier
	v_mfma_f32_16x16x32_bf16 v[54:57], v[192:195], v[146:149], v[54:57]
	v_mfma_f32_16x16x32_bf16 v[50:53], v[206:209], v[146:149], v[50:53]
	v_mfma_f32_16x16x32_bf16 v[38:41], v[192:195], v[154:157], v[38:41]
	v_mfma_f32_16x16x32_bf16 v[34:37], v[206:209], v[154:157], v[34:37]
	v_mfma_f32_16x16x32_bf16 v[22:25], v[192:195], v[174:177], v[22:25]
	v_mfma_f32_16x16x32_bf16 v[18:21], v[206:209], v[174:177], v[18:21]
	v_mfma_f32_16x16x32_bf16 v[6:9], v[192:195], v[184:187], v[6:9]
	v_mfma_f32_16x16x32_bf16 v[2:5], v[206:209], v[184:187], v[2:5]
	v_mfma_f32_16x16x32_bf16 v[54:57], v[198:201], v[150:153], v[54:57]
	v_mfma_f32_16x16x32_bf16 v[50:53], v[210:213], v[150:153], v[50:53]
	v_mfma_f32_16x16x32_bf16 v[38:41], v[198:201], v[170:173], v[38:41]
	v_mfma_f32_16x16x32_bf16 v[34:37], v[210:213], v[170:173], v[34:37]
	v_mfma_f32_16x16x32_bf16 v[22:25], v[198:201], v[178:181], v[22:25]
	v_mfma_f32_16x16x32_bf16 v[18:21], v[210:213], v[178:181], v[18:21]
	v_mfma_f32_16x16x32_bf16 v[6:9], v[198:201], v[188:191], v[6:9]
	v_mfma_f32_16x16x32_bf16 v[2:5], v[210:213], v[188:191], v[2:5]
	s_add_u32 s39, s39, 0x100
	s_addc_u32 s40, s40, 0
	s_cmp_ge_i32 s41, s87
	s_mov_b64 s[26:27], s[28:29]
	s_mov_b32 s30, s41
	s_barrier
	s_cbranch_scc0 .LBB0_1432
	v_mbcnt_lo_u32_b32 v0, -1, 0
	v_mbcnt_hi_u32_b32 v0, -1, v0
	s_cmp_eq_u32 s86, 0
	v_and_or_b32 v170, v0, 15, s65
	v_lshrrev_b32_e32 v0, 1, v0
	v_and_or_b32 v184, v0, 24, s66
	v_or_b32_e32 v146, 16, v170
	v_or_b32_e32 v174, 32, v170
	v_or_b32_e32 v172, 48, v170
	v_ashrrev_i32_e32 v171, 31, v170
	v_lshlrev_b32_e32 v0, 1, v184
	v_ashrrev_i32_e32 v147, 31, v146
	v_ashrrev_i32_e32 v175, 31, v174
	v_ashrrev_i32_e32 v173, 31, v172
	s_cbranch_scc1 .LBB0_1435
; __device__ __forceinline__ unsigned pk_bf16(float lo, float hi) { unsigned r; asm volatile("v_cvt_pk_bf16_f32 %0, %1, %2" : "=v"(r) : "v"(lo), "v"(hi)); return r; }
;     __device__ __forceinline__ void operator()(const f32x4 (&acc)[2][2][4][2], const Unit& u, int wr, int wc, int fr, int fq) const {
;     ...
;             for (int ai = 0; ai < 2; ++ai)
; #pragma unroll
;                 for (int m = 0; m < 4; ++m) { bf16_t* op = (bf16_t*)u.o + (size_t)(row0 + ai * HALF + m * 16) * 1024 + col0;
; #pragma unroll
;                     for (int bj = 0; bj < 2; ++bj) { const f32x4 v0 = acc[ai][bj][m][0], v1 = acc[ai][bj][m][1];
;                         u32x4 w; w.x = pk_bf16(v0[0], v0[1]); w.y = pk_bf16(v0[2], v0[3]); w.z = pk_bf16(v1[0], v1[1]); w.w = pk_bf16(v1[2], v1[3]); st16_wt(op + bj * HALF, w); } }
	v_lshlrev_b64 v[106:107], 11, v[170:171]
	v_lshl_add_u64 v[106:107], s[8:9], 0, v[106:107]
	v_lshl_add_u64 v[106:107], v[106:107], 0, v[0:1]
	v_cvt_pk_bf16_f32 v108, v142, v143
	v_cvt_pk_bf16_f32 v109, v144, v145
	v_cvt_pk_bf16_f32 v110, v138, v139
	v_cvt_pk_bf16_f32 v111, v140, v141
	global_store_dwordx4 v[106:107], v[108:111], off
	s_mov_b64 s[4:5], 0x40000
	s_nop 0
	v_cvt_pk_bf16_f32 v108, v134, v135
	v_cvt_pk_bf16_f32 v109, v136, v137
	v_cvt_pk_bf16_f32 v110, v130, v131
	v_cvt_pk_bf16_f32 v111, v132, v133
	global_store_dwordx4 v[106:107], v[108:111], off offset:256
	s_nop 1
	v_lshlrev_b64 v[108:109], 11, v[146:147]
	v_lshl_add_u64 v[108:109], s[8:9], 0, v[108:109]
	v_lshl_add_u64 v[112:113], v[108:109], 0, v[0:1]
	v_cvt_pk_bf16_f32 v108, v118, v119
	v_cvt_pk_bf16_f32 v109, v120, v121
	v_cvt_pk_bf16_f32 v110, v114, v115
	v_cvt_pk_bf16_f32 v111, v116, v117
	global_store_dwordx4 v[112:113], v[108:111], off
	s_nop 1
	v_cvt_pk_bf16_f32 v108, v102, v103
	v_cvt_pk_bf16_f32 v109, v104, v105
	v_cvt_pk_bf16_f32 v110, v98, v99
	v_cvt_pk_bf16_f32 v111, v100, v101
	global_store_dwordx4 v[112:113], v[108:111], off offset:256
	s_nop 1
	v_lshlrev_b64 v[108:109], 11, v[174:175]
	v_lshl_add_u64 v[108:109], s[8:9], 0, v[108:109]
	v_lshl_add_u64 v[112:113], v[108:109], 0, v[0:1]
	v_cvt_pk_bf16_f32 v108, v94, v95
	v_cvt_pk_bf16_f32 v109, v96, v97
	v_cvt_pk_bf16_f32 v110, v90, v91
	v_cvt_pk_bf16_f32 v111, v92, v93
	global_store_dwordx4 v[112:113], v[108:111], off
	s_nop 1
	v_cvt_pk_bf16_f32 v108, v86, v87
	v_cvt_pk_bf16_f32 v109, v88, v89
	v_cvt_pk_bf16_f32 v110, v82, v83
	v_cvt_pk_bf16_f32 v111, v84, v85
	global_store_dwordx4 v[112:113], v[108:111], off offset:256
	s_nop 1
	v_lshlrev_b64 v[108:109], 11, v[172:173]
	v_lshl_add_u64 v[108:109], s[8:9], 0, v[108:109]
	v_lshl_add_u64 v[112:113], v[108:109], 0, v[0:1]
	v_cvt_pk_bf16_f32 v108, v78, v79
	v_cvt_pk_bf16_f32 v109, v80, v81
	v_cvt_pk_bf16_f32 v110, v74, v75
	v_cvt_pk_bf16_f32 v111, v76, v77
	global_store_dwordx4 v[112:113], v[108:111], off
	s_nop 1
	v_cvt_pk_bf16_f32 v108, v70, v71
	v_cvt_pk_bf16_f32 v109, v72, v73
	v_cvt_pk_bf16_f32 v110, v66, v67
	v_cvt_pk_bf16_f32 v111, v68, v69
	global_store_dwordx4 v[112:113], v[108:111], off offset:256
	v_lshl_add_u64 v[112:113], v[106:107], 0, s[4:5]
	s_mov_b32 s4, 0x40000
	v_add_co_u32_e32 v122, vcc, s4, v106
	v_cvt_pk_bf16_f32 v108, v62, v63
	v_cvt_pk_bf16_f32 v109, v64, v65
	v_cvt_pk_bf16_f32 v110, v58, v59
	v_cvt_pk_bf16_f32 v111, v60, v61
	s_nop 1
	v_addc_co_u32_e32 v123, vcc, 0, v107, vcc
	s_mov_b64 s[4:5], 0x48000
	global_store_dwordx4 v[122:123], v[108:111], off
	s_nop 1
	v_cvt_pk_bf16_f32 v108, v54, v55
	v_cvt_pk_bf16_f32 v109, v56, v57
	v_cvt_pk_bf16_f32 v110, v50, v51
	v_cvt_pk_bf16_f32 v111, v52, v53
	global_store_dwordx4 v[112:113], v[108:111], off offset:256
	v_lshl_add_u64 v[112:113], v[106:107], 0, s[4:5]
	s_mov_b32 s4, 0x48000
	v_add_co_u32_e32 v122, vcc, s4, v106
	v_cvt_pk_bf16_f32 v108, v46, v47
	v_cvt_pk_bf16_f32 v109, v48, v49
	v_cvt_pk_bf16_f32 v110, v42, v43
	v_cvt_pk_bf16_f32 v111, v44, v45
	s_nop 1
	v_addc_co_u32_e32 v123, vcc, 0, v107, vcc
	s_mov_b64 s[4:5], 0x50000
	global_store_dwordx4 v[122:123], v[108:111], off
	s_nop 1
	v_cvt_pk_bf16_f32 v108, v38, v39
	v_cvt_pk_bf16_f32 v109, v40, v41
	v_cvt_pk_bf16_f32 v110, v34, v35
	v_cvt_pk_bf16_f32 v111, v36, v37
	global_store_dwordx4 v[112:113], v[108:111], off offset:256
	v_lshl_add_u64 v[112:113], v[106:107], 0, s[4:5]
	s_mov_b32 s4, 0x50000
	v_add_co_u32_e32 v122, vcc, s4, v106
	v_cvt_pk_bf16_f32 v108, v30, v31
	v_cvt_pk_bf16_f32 v109, v32, v33
	v_cvt_pk_bf16_f32 v110, v26, v27
	v_cvt_pk_bf16_f32 v111, v28, v29
	s_nop 1
	v_addc_co_u32_e32 v123, vcc, 0, v107, vcc
	s_mov_b64 s[4:5], 0x58000
	global_store_dwordx4 v[122:123], v[108:111], off
	s_nop 1
	v_cvt_pk_bf16_f32 v108, v22, v23
	v_cvt_pk_bf16_f32 v109, v24, v25
	v_cvt_pk_bf16_f32 v110, v18, v19
	v_cvt_pk_bf16_f32 v111, v20, v21
	global_store_dwordx4 v[112:113], v[108:111], off offset:256
	v_lshl_add_u64 v[112:113], v[106:107], 0, s[4:5]
	s_mov_b32 s4, 0x58000
	v_add_co_u32_e32 v106, vcc, s4, v106
	v_cvt_pk_bf16_f32 v108, v14, v15
	v_cvt_pk_bf16_f32 v109, v16, v17
	s_mov_b64 s[4:5], 0
	s_nop 0
	v_addc_co_u32_e32 v107, vcc, 0, v107, vcc
	v_cvt_pk_bf16_f32 v110, v10, v11
	v_cvt_pk_bf16_f32 v111, v12, v13
	global_store_dwordx4 v[106:107], v[108:111], off
	v_cvt_pk_bf16_f32 v106, v6, v7
	v_cvt_pk_bf16_f32 v107, v8, v9
	s_nop 1
	v_cvt_pk_bf16_f32 v108, v2, v3
	v_cvt_pk_bf16_f32 v109, v4, v5
	global_store_dwordx4 v[112:113], v[106:109], off offset:256
	s_branch .LBB0_1436
